# speedup vs baseline: 1.0028x; 1.0028x over previous
; __device__ __forceinline__ float step_compute(float (&S)[4], const StepOp& o) {
;     float d1 = vmul(S[0], o.kk[0]), d2 = vmul(S[0], o.wr[0]), e1 = vmul(S[1], o.kk[1]), e2 = vmul(S[1], o.wr[1]);
;     d1 = vfma(S[2], o.kk[2], d1); d2 = vfma(S[2], o.wr[2], d2); e1 = vfma(S[3], o.kk[3], e1); e2 = vfma(S[3], o.wr[3], e2);
;     d1 = vadd(d1, e1); d2 = vadd(d2, e2);
;     float t0, t1, t2, t3;
;     asm volatile(
;         "v_mul_f32 %[t0], %[s0], %[w0]\n\t"
;         "v_mul_f32 %[t1], %[s1], %[w1]\n\t"
;         "v_add_f32_dpp %[d1], %[d1], %[d1] quad_perm:[1,0,3,2] row_mask:0xf bank_mask:0xf bound_ctrl:1\n\t"
;         "v_add_f32_dpp %[d2], %[d2], %[d2] quad_perm:[1,0,3,2] row_mask:0xf bank_mask:0xf bound_ctrl:1\n\t"
;         "v_mul_f32 %[t2], %[s2], %[w2]\n\t"
;         "v_add_f32_dpp %[d1], %[d1], %[d1] quad_perm:[2,3,0,1] row_mask:0xf bank_mask:0xf bound_ctrl:1\n\t"
;         "v_add_f32_dpp %[d2], %[d2], %[d2] quad_perm:[2,3,0,1] row_mask:0xf bank_mask:0xf bound_ctrl:1\n\t"
;         "v_mul_f32 %[t3], %[s3], %[w3]\n\t"
;         "v_add_f32_dpp %[d1], %[d1], %[d1] row_half_mirror row_mask:0xf bank_mask:0xf bound_ctrl:1\n\t"
;         "v_add_f32_dpp %[d2], %[d2], %[d2] row_half_mirror row_mask:0xf bank_mask:0xf bound_ctrl:1\n\t"
;         "v_fma_f32 %[t0], %[v], %[k0], %[t0]\n\t"
;         "v_add_f32_dpp %[d1], %[d1], %[d1] row_mirror row_mask:0xf bank_mask:0xf bound_ctrl:1\n\t"
;         "v_add_f32_dpp %[d2], %[d2], %[d2] row_mirror row_mask:0xf bank_mask:0xf bound_ctrl:1\n\t"
;         "v_fma_f32 %[t1], %[v], %[k1], %[t1]\n\t"
;         "v_fma_f32 %[t2], %[v], %[k2], %[t2]\n\t"
;         "v_fma_f32 %[t3], %[v], %[k3], %[t3]"
; __device__ __forceinline__ void scan_quarter(LAS unsigned char* lds, const ScanConst& C, int m0, int T, int h, int quarter, const float* shift_prev  , const float* S0p  , float* Sout, const float* cWg, const float* cWu, const float* cWd, bf16* cWGU, bf16* cWD, int& conv_next, int conv_stride, int wa ...
;     ...
;             step_load(A, sp, qp);
; #pragma unroll
;             for (int t = 0; t < TC; t += 2) {
;                 step_load(B, sp + (t + 1) * STEP_F, qp + (t + 1) * STEP_F);
;                 yb[t * 16] = step_compute(S, A);
;                 if (t + 2 < TC) step_load(A, sp + (t + 2) * STEP_F, qp + (t + 2) * STEP_F);
;                 yb[(t + 1) * 16] = step_compute(S, B);
;             }
.LBB0_774:
	v_cndmask_b32_e64 v2, 0, 1, s[50:51]
	v_cmp_ne_u32_e64 s[8:9], 1, v2
	s_andn2_b64 vcc, exec, s[50:51]
	s_mov_b64 s[78:79], -1
	s_cbranch_vccnz .LBB0_776
	s_and_b64 s[78:79], s[74:75], exec
	s_cselect_b32 s10, 0, s91
	v_add_u32_e32 v3, s10, v149
	s_cselect_b32 s10, s93, s92
	v_add_u32_e32 v4, s10, v150
	ds_read_b128 v[160:163], v3
	ds_read_b128 v[168:171], v3 offset:256
	ds_read_b128 v[172:175], v3 offset:512
	ds_read_b128 v[180:183], v3 offset:1024
	ds_read_b128 v[184:187], v4
	ds_read_b128 v[176:179], v3 offset:768
	v_add_u32_e32 v2, s42, v148
	s_mov_b64 s[78:79], 0
	v_mbcnt_lo_u32_b32 v115, -1, 0
	v_mbcnt_hi_u32_b32 v115, -1, v115
	v_and_b32_e32 v115, 4, v115
	v_xor_b32_e32 v115, 4, v115
	v_mul_u32_u24_e32 v115, 0x2700, v115
	v_add_u32_e32 v2, v2, v115
	ds_read_b128 v[188:191], v3 offset:1536
	ds_read_b128 v[192:195], v3 offset:1792
	ds_read_b128 v[196:199], v3 offset:2048
	ds_read_b128 v[204:207], v3 offset:2560
	ds_read_b128 v[208:211], v4 offset:1536
	ds_read_b128 v[200:203], v3 offset:2304
	s_waitcnt lgkmcnt(6)
	v_mul_f32 v160, v38, v160
	v_mul_f32 v168, v38, v168
	v_fma_f32 v160, v39, v161, v160
	v_fma_f32 v168, v39, v169, v168
	v_fma_f32 v160, v40, v162, v160
	v_fma_f32 v168, v40, v170, v168
	v_fma_f32 v160, v41, v163, v160
	v_fma_f32 v168, v41, v171, v168
	v_mul_f32 v172, v38, v172
	v_add_f32_dpp v160, v160, v160 row_half_mirror row_mask:0xf bank_mask:0x5
	v_add_f32_dpp v160, v168, v168 row_half_mirror row_mask:0xf bank_mask:0xa
	v_mul_f32 v173, v39, v173
	v_mul_f32 v174, v40, v174
	v_add_f32_dpp v160, v160, v160 quad_perm:[1,0,3,2] row_mask:0xf bank_mask:0xf
	v_mul_f32 v175, v41, v175
	v_fma_f32 v172, v184, v180, v172
	v_add_f32_dpp v160, v160, v160 quad_perm:[2,3,0,1] row_mask:0xf bank_mask:0xf
	v_fma_f32 v173, v184, v181, v173
	v_fma_f32 v174, v184, v182, v174
	v_add_f32_dpp v160, v160, v160 row_ror:8 row_mask:0xf bank_mask:0xf
	v_fma_f32 v175, v184, v183, v175
	v_fma_f32 v168, v184, v186, v160
	v_mov_b32_dpp v160, v160 row_half_mirror row_mask:0xf bank_mask:0xa
	ds_read_b128 v[180:183], v3 offset:4096
	v_fma_f32 v159, -v160, v176, v172
	v_fma_f32 v164, -v160, v177, v173
	v_fma_f32 v165, -v160, v178, v174
	v_fma_f32 v167, -v160, v179, v175
	v_fma_f32 v168, -v160, v185, v168
	ds_read_b128 v[160:163], v3 offset:3072
	ds_write_b32 v2, v168
	ds_read_b128 v[168:171], v3 offset:3328
	ds_read_b128 v[172:175], v3 offset:3584
	ds_read_b128 v[184:187], v4 offset:3072
	ds_read_b128 v[176:179], v3 offset:3840
	s_waitcnt lgkmcnt(7)
	v_mul_f32 v188, v159, v188
	v_mul_f32 v192, v159, v192
	v_fma_f32 v188, v164, v189, v188
	v_fma_f32 v192, v164, v193, v192
	v_fma_f32 v188, v165, v190, v188
	v_fma_f32 v192, v165, v194, v192
	v_fma_f32 v188, v167, v191, v188
	v_fma_f32 v192, v167, v195, v192
	v_mul_f32 v196, v159, v196
	v_add_f32_dpp v188, v188, v188 row_half_mirror row_mask:0xf bank_mask:0x5
	v_add_f32_dpp v188, v192, v192 row_half_mirror row_mask:0xf bank_mask:0xa
	v_mul_f32 v197, v164, v197
	v_mul_f32 v198, v165, v198
	v_add_f32_dpp v188, v188, v188 quad_perm:[1,0,3,2] row_mask:0xf bank_mask:0xf
	v_mul_f32 v199, v167, v199
	v_fma_f32 v196, v208, v204, v196
	v_add_f32_dpp v188, v188, v188 quad_perm:[2,3,0,1] row_mask:0xf bank_mask:0xf
	v_fma_f32 v197, v208, v205, v197
	v_fma_f32 v198, v208, v206, v198
	v_add_f32_dpp v188, v188, v188 row_ror:8 row_mask:0xf bank_mask:0xf
	v_fma_f32 v199, v208, v207, v199
	v_fma_f32 v192, v208, v210, v188
	v_mov_b32_dpp v188, v188 row_half_mirror row_mask:0xf bank_mask:0xa
	ds_read_b128 v[204:207], v3 offset:5632
	v_fma_f32 v159, -v188, v200, v196
	v_fma_f32 v164, -v188, v201, v197
	v_fma_f32 v165, -v188, v202, v198
	v_fma_f32 v167, -v188, v203, v199
	v_fma_f32 v192, -v188, v209, v192
	ds_read_b128 v[188:191], v3 offset:4608
	ds_write_b32 v2, v192 offset:64
	ds_read_b128 v[192:195], v3 offset:4864
	ds_read_b128 v[196:199], v3 offset:5120
	ds_read_b128 v[208:211], v4 offset:4608
	ds_read_b128 v[200:203], v3 offset:5376
	s_waitcnt lgkmcnt(7)
	v_mul_f32 v160, v159, v160
	v_mul_f32 v168, v159, v168
	v_fma_f32 v160, v164, v161, v160
	v_fma_f32 v168, v164, v169, v168
	v_fma_f32 v160, v165, v162, v160
	v_fma_f32 v168, v165, v170, v168
	v_fma_f32 v160, v167, v163, v160
	v_fma_f32 v168, v167, v171, v168
	v_mul_f32 v172, v159, v172
	v_add_f32_dpp v160, v160, v160 row_half_mirror row_mask:0xf bank_mask:0x5
	v_add_f32_dpp v160, v168, v168 row_half_mirror row_mask:0xf bank_mask:0xa
	v_mul_f32 v173, v164, v173
	v_mul_f32 v174, v165, v174
	v_add_f32_dpp v160, v160, v160 quad_perm:[1,0,3,2] row_mask:0xf bank_mask:0xf
	v_mul_f32 v175, v167, v175
	v_fma_f32 v172, v184, v180, v172
	v_add_f32_dpp v160, v160, v160 quad_perm:[2,3,0,1] row_mask:0xf bank_mask:0xf
	v_fma_f32 v173, v184, v181, v173
	v_fma_f32 v174, v184, v182, v174
	v_add_f32_dpp v160, v160, v160 row_ror:8 row_mask:0xf bank_mask:0xf
	v_fma_f32 v175, v184, v183, v175
	v_fma_f32 v168, v184, v186, v160
	v_mov_b32_dpp v160, v160 row_half_mirror row_mask:0xf bank_mask:0xa
	ds_read_b128 v[180:183], v3 offset:7168
	v_fma_f32 v159, -v160, v176, v172
	v_fma_f32 v164, -v160, v177, v173
	v_fma_f32 v165, -v160, v178, v174
	v_fma_f32 v167, -v160, v179, v175
	v_fma_f32 v168, -v160, v185, v168
	ds_read_b128 v[160:163], v3 offset:6144
	ds_write_b32 v2, v168 offset:128
	ds_read_b128 v[168:171], v3 offset:6400
	ds_read_b128 v[172:175], v3 offset:6656
	ds_read_b128 v[184:187], v4 offset:6144
	ds_read_b128 v[176:179], v3 offset:6912
	s_waitcnt lgkmcnt(7)
; __device__ __forceinline__ float vfma(float a, float b, float c) { float d; asm("v_fma_f32 %0, %1, %2, %3" : "=v"(d) : "v"(a), "v"(b), "v"(c)); return d; }
; __device__ __forceinline__ float vnfma(float a, float b, float c) { float d; asm("v_fma_f32 %0, -%1, %2, %3" : "=v"(d) : "v"(a), "v"(b), "v"(c)); return d; }
; __device__ __forceinline__ float vmul(float a, float b) { float d; asm("v_mul_f32 %0, %1, %2" : "=v"(d) : "v"(a), "v"(b)); return d; }
; __device__ __forceinline__ float vadd(float a, float b) { float d; asm("v_add_f32 %0, %1, %2" : "=v"(d) : "v"(a), "v"(b)); return d; }
; __device__ __forceinline__ float step_compute(float (&S)[4], const StepOp& o) {
;     float d1 = vmul(S[0], o.kk[0]), d2 = vmul(S[0], o.wr[0]), e1 = vmul(S[1], o.kk[1]), e2 = vmul(S[1], o.wr[1]);
;     d1 = vfma(S[2], o.kk[2], d1); d2 = vfma(S[2], o.wr[2], d2); e1 = vfma(S[3], o.kk[3], e1); e2 = vfma(S[3], o.wr[3], e2);
;     d1 = vadd(d1, e1); d2 = vadd(d2, e2);
;     float t0, t1, t2, t3;
;     asm volatile(
;         "v_mul_f32 %[t0], %[s0], %[w0]\n\t"
;         "v_mul_f32 %[t1], %[s1], %[w1]\n\t"
;         "v_add_f32_dpp %[d1], %[d1], %[d1] quad_perm:[1,0,3,2] row_mask:0xf bank_mask:0xf bound_ctrl:1\n\t"
;         "v_add_f32_dpp %[d2], %[d2], %[d2] quad_perm:[1,0,3,2] row_mask:0xf bank_mask:0xf bound_ctrl:1\n\t"
;         "v_mul_f32 %[t2], %[s2], %[w2]\n\t"
;         "v_add_f32_dpp %[d1], %[d1], %[d1] quad_perm:[2,3,0,1] row_mask:0xf bank_mask:0xf bound_ctrl:1\n\t"
;         "v_add_f32_dpp %[d2], %[d2], %[d2] quad_perm:[2,3,0,1] row_mask:0xf bank_mask:0xf bound_ctrl:1\n\t"
;         "v_mul_f32 %[t3], %[s3], %[w3]\n\t"
;         "v_add_f32_dpp %[d1], %[d1], %[d1] row_half_mirror row_mask:0xf bank_mask:0xf bound_ctrl:1\n\t"
;         "v_add_f32_dpp %[d2], %[d2], %[d2] row_half_mirror row_mask:0xf bank_mask:0xf bound_ctrl:1\n\t"
;         "v_fma_f32 %[t0], %[v], %[k0], %[t0]\n\t"
;         "v_add_f32_dpp %[d1], %[d1], %[d1] row_mirror row_mask:0xf bank_mask:0xf bound_ctrl:1\n\t"
;         "v_add_f32_dpp %[d2], %[d2], %[d2] row_mirror row_mask:0xf bank_mask:0xf bound_ctrl:1\n\t"
;         "v_fma_f32 %[t1], %[v], %[k1], %[t1]\n\t"
;         "v_fma_f32 %[t2], %[v], %[k2], %[t2]\n\t"
;         "v_fma_f32 %[t3], %[v], %[k3], %[t3]"
;         : [t0] "=&v"(t0), [t1] "=&v"(t1), [t2] "=&v"(t2), [t3] "=&v"(t3), [d1] "+v"(d1), [d2] "+v"(d2)
	v_mul_f32 v188, v159, v188
	v_mul_f32 v192, v159, v192
	v_fma_f32 v188, v164, v189, v188
	v_fma_f32 v192, v164, v193, v192
	v_fma_f32 v188, v165, v190, v188
	v_fma_f32 v192, v165, v194, v192
	v_fma_f32 v188, v167, v191, v188
	v_fma_f32 v192, v167, v195, v192
	v_mul_f32 v196, v159, v196
	v_add_f32_dpp v188, v188, v188 row_half_mirror row_mask:0xf bank_mask:0x5
	v_add_f32_dpp v188, v192, v192 row_half_mirror row_mask:0xf bank_mask:0xa
	v_mul_f32 v197, v164, v197
	v_mul_f32 v198, v165, v198
	v_add_f32_dpp v188, v188, v188 quad_perm:[1,0,3,2] row_mask:0xf bank_mask:0xf
	v_mul_f32 v199, v167, v199
	v_fma_f32 v196, v208, v204, v196
	v_add_f32_dpp v188, v188, v188 quad_perm:[2,3,0,1] row_mask:0xf bank_mask:0xf
	v_fma_f32 v197, v208, v205, v197
	v_fma_f32 v198, v208, v206, v198
	v_add_f32_dpp v188, v188, v188 row_ror:8 row_mask:0xf bank_mask:0xf
	v_fma_f32 v199, v208, v207, v199
	v_fma_f32 v192, v208, v210, v188
	v_mov_b32_dpp v188, v188 row_half_mirror row_mask:0xf bank_mask:0xa
	ds_read_b128 v[204:207], v3 offset:8704
	v_fma_f32 v159, -v188, v200, v196
	v_fma_f32 v164, -v188, v201, v197
	v_fma_f32 v165, -v188, v202, v198
	v_fma_f32 v167, -v188, v203, v199
	v_fma_f32 v192, -v188, v209, v192
	ds_read_b128 v[188:191], v3 offset:7680
	ds_write_b32 v2, v192 offset:192
	ds_read_b128 v[192:195], v3 offset:7936
	ds_read_b128 v[196:199], v3 offset:8192
	ds_read_b128 v[208:211], v4 offset:7680
	ds_read_b128 v[200:203], v3 offset:8448
	s_waitcnt lgkmcnt(7)
	v_mul_f32 v160, v159, v160
	v_mul_f32 v168, v159, v168
	v_fma_f32 v160, v164, v161, v160
	v_fma_f32 v168, v164, v169, v168
	v_fma_f32 v160, v165, v162, v160
	v_fma_f32 v168, v165, v170, v168
	v_fma_f32 v160, v167, v163, v160
	v_fma_f32 v168, v167, v171, v168
	v_mul_f32 v172, v159, v172
	v_add_f32_dpp v160, v160, v160 row_half_mirror row_mask:0xf bank_mask:0x5
	v_add_f32_dpp v160, v168, v168 row_half_mirror row_mask:0xf bank_mask:0xa
	v_mul_f32 v173, v164, v173
	v_mul_f32 v174, v165, v174
	v_add_f32_dpp v160, v160, v160 quad_perm:[1,0,3,2] row_mask:0xf bank_mask:0xf
	v_mul_f32 v175, v167, v175
	v_fma_f32 v172, v184, v180, v172
	v_add_f32_dpp v160, v160, v160 quad_perm:[2,3,0,1] row_mask:0xf bank_mask:0xf
	v_fma_f32 v173, v184, v181, v173
	v_fma_f32 v174, v184, v182, v174
	v_add_f32_dpp v160, v160, v160 row_ror:8 row_mask:0xf bank_mask:0xf
	v_fma_f32 v175, v184, v183, v175
	v_fma_f32 v168, v184, v186, v160
	v_mov_b32_dpp v160, v160 row_half_mirror row_mask:0xf bank_mask:0xa
	ds_read_b128 v[180:183], v3 offset:10240
	v_fma_f32 v159, -v160, v176, v172
	v_fma_f32 v164, -v160, v177, v173
	v_fma_f32 v165, -v160, v178, v174
	v_fma_f32 v167, -v160, v179, v175
	v_fma_f32 v168, -v160, v185, v168
	ds_read_b128 v[160:163], v3 offset:9216
	ds_write_b32 v2, v168 offset:256
	ds_read_b128 v[168:171], v3 offset:9472
	ds_read_b128 v[172:175], v3 offset:9728
	ds_read_b128 v[184:187], v4 offset:9216
	ds_read_b128 v[176:179], v3 offset:9984
	s_waitcnt lgkmcnt(7)
	v_mul_f32 v188, v159, v188
	v_mul_f32 v192, v159, v192
	v_fma_f32 v188, v164, v189, v188
	v_fma_f32 v192, v164, v193, v192
	v_fma_f32 v188, v165, v190, v188
	v_fma_f32 v192, v165, v194, v192
	v_fma_f32 v188, v167, v191, v188
	v_fma_f32 v192, v167, v195, v192
	v_mul_f32 v196, v159, v196
	v_add_f32_dpp v188, v188, v188 row_half_mirror row_mask:0xf bank_mask:0x5
	v_add_f32_dpp v188, v192, v192 row_half_mirror row_mask:0xf bank_mask:0xa
	v_mul_f32 v197, v164, v197
	v_mul_f32 v198, v165, v198
	v_add_f32_dpp v188, v188, v188 quad_perm:[1,0,3,2] row_mask:0xf bank_mask:0xf
	v_mul_f32 v199, v167, v199
	v_fma_f32 v196, v208, v204, v196
	v_add_f32_dpp v188, v188, v188 quad_perm:[2,3,0,1] row_mask:0xf bank_mask:0xf
	v_fma_f32 v197, v208, v205, v197
	v_fma_f32 v198, v208, v206, v198
	v_add_f32_dpp v188, v188, v188 row_ror:8 row_mask:0xf bank_mask:0xf
	v_fma_f32 v199, v208, v207, v199
	v_fma_f32 v192, v208, v210, v188
	v_mov_b32_dpp v188, v188 row_half_mirror row_mask:0xf bank_mask:0xa
	ds_read_b128 v[204:207], v3 offset:11776
	v_fma_f32 v159, -v188, v200, v196
	v_fma_f32 v164, -v188, v201, v197
	v_fma_f32 v165, -v188, v202, v198
	v_fma_f32 v167, -v188, v203, v199
	v_fma_f32 v192, -v188, v209, v192
	ds_read_b128 v[188:191], v3 offset:10752
	ds_write_b32 v2, v192 offset:320
	ds_read_b128 v[192:195], v3 offset:11008
	ds_read_b128 v[196:199], v3 offset:11264
	ds_read_b128 v[208:211], v4 offset:10752
	ds_read_b128 v[200:203], v3 offset:11520
	s_waitcnt lgkmcnt(7)
	v_mul_f32 v160, v159, v160
	v_mul_f32 v168, v159, v168
	v_fma_f32 v160, v164, v161, v160
	v_fma_f32 v168, v164, v169, v168
	v_fma_f32 v160, v165, v162, v160
	v_fma_f32 v168, v165, v170, v168
	v_fma_f32 v160, v167, v163, v160
	v_fma_f32 v168, v167, v171, v168
	v_mul_f32 v172, v159, v172
	v_add_f32_dpp v160, v160, v160 row_half_mirror row_mask:0xf bank_mask:0x5
	v_add_f32_dpp v160, v168, v168 row_half_mirror row_mask:0xf bank_mask:0xa
	v_mul_f32 v173, v164, v173
	v_mul_f32 v174, v165, v174
	v_add_f32_dpp v160, v160, v160 quad_perm:[1,0,3,2] row_mask:0xf bank_mask:0xf
	v_mul_f32 v175, v167, v175
	v_fma_f32 v172, v184, v180, v172
	v_add_f32_dpp v160, v160, v160 quad_perm:[2,3,0,1] row_mask:0xf bank_mask:0xf
	v_fma_f32 v173, v184, v181, v173
	v_fma_f32 v174, v184, v182, v174
	v_add_f32_dpp v160, v160, v160 row_ror:8 row_mask:0xf bank_mask:0xf
	v_fma_f32 v175, v184, v183, v175
	v_fma_f32 v168, v184, v186, v160
	v_mov_b32_dpp v160, v160 row_half_mirror row_mask:0xf bank_mask:0xa
	ds_read_b128 v[180:183], v3 offset:13312
	v_fma_f32 v159, -v160, v176, v172
	v_fma_f32 v164, -v160, v177, v173
	v_fma_f32 v165, -v160, v178, v174
	v_fma_f32 v167, -v160, v179, v175
	v_fma_f32 v168, -v160, v185, v168
	ds_read_b128 v[160:163], v3 offset:12288
	ds_write_b32 v2, v168 offset:384
	ds_read_b128 v[168:171], v3 offset:12544
	ds_read_b128 v[172:175], v3 offset:12800
	ds_read_b128 v[184:187], v4 offset:12288
	ds_read_b128 v[176:179], v3 offset:13056
	s_waitcnt lgkmcnt(7)
; __device__ __forceinline__ float vfma(float a, float b, float c) { float d; asm("v_fma_f32 %0, %1, %2, %3" : "=v"(d) : "v"(a), "v"(b), "v"(c)); return d; }
; __device__ __forceinline__ float vnfma(float a, float b, float c) { float d; asm("v_fma_f32 %0, -%1, %2, %3" : "=v"(d) : "v"(a), "v"(b), "v"(c)); return d; }
; __device__ __forceinline__ float vmul(float a, float b) { float d; asm("v_mul_f32 %0, %1, %2" : "=v"(d) : "v"(a), "v"(b)); return d; }
; __device__ __forceinline__ float vadd(float a, float b) { float d; asm("v_add_f32 %0, %1, %2" : "=v"(d) : "v"(a), "v"(b)); return d; }
; __device__ __forceinline__ float step_compute(float (&S)[4], const StepOp& o) {
;     float d1 = vmul(S[0], o.kk[0]), d2 = vmul(S[0], o.wr[0]), e1 = vmul(S[1], o.kk[1]), e2 = vmul(S[1], o.wr[1]);
;     d1 = vfma(S[2], o.kk[2], d1); d2 = vfma(S[2], o.wr[2], d2); e1 = vfma(S[3], o.kk[3], e1); e2 = vfma(S[3], o.wr[3], e2);
;     d1 = vadd(d1, e1); d2 = vadd(d2, e2);
;     float t0, t1, t2, t3;
;     asm volatile(
;         "v_mul_f32 %[t0], %[s0], %[w0]\n\t"
;         "v_mul_f32 %[t1], %[s1], %[w1]\n\t"
;         "v_add_f32_dpp %[d1], %[d1], %[d1] quad_perm:[1,0,3,2] row_mask:0xf bank_mask:0xf bound_ctrl:1\n\t"
;         "v_add_f32_dpp %[d2], %[d2], %[d2] quad_perm:[1,0,3,2] row_mask:0xf bank_mask:0xf bound_ctrl:1\n\t"
;         "v_mul_f32 %[t2], %[s2], %[w2]\n\t"
;         "v_add_f32_dpp %[d1], %[d1], %[d1] quad_perm:[2,3,0,1] row_mask:0xf bank_mask:0xf bound_ctrl:1\n\t"
;         "v_add_f32_dpp %[d2], %[d2], %[d2] quad_perm:[2,3,0,1] row_mask:0xf bank_mask:0xf bound_ctrl:1\n\t"
;         "v_mul_f32 %[t3], %[s3], %[w3]\n\t"
;         "v_add_f32_dpp %[d1], %[d1], %[d1] row_half_mirror row_mask:0xf bank_mask:0xf bound_ctrl:1\n\t"
;         "v_add_f32_dpp %[d2], %[d2], %[d2] row_half_mirror row_mask:0xf bank_mask:0xf bound_ctrl:1\n\t"
;         "v_fma_f32 %[t0], %[v], %[k0], %[t0]\n\t"
;         "v_add_f32_dpp %[d1], %[d1], %[d1] row_mirror row_mask:0xf bank_mask:0xf bound_ctrl:1\n\t"
;         "v_add_f32_dpp %[d2], %[d2], %[d2] row_mirror row_mask:0xf bank_mask:0xf bound_ctrl:1\n\t"
;         "v_fma_f32 %[t1], %[v], %[k1], %[t1]\n\t"
;         "v_fma_f32 %[t2], %[v], %[k2], %[t2]\n\t"
;         "v_fma_f32 %[t3], %[v], %[k3], %[t3]"
;         : [t0] "=&v"(t0), [t1] "=&v"(t1), [t2] "=&v"(t2), [t3] "=&v"(t3), [d1] "+v"(d1), [d2] "+v"(d2)
	v_mul_f32 v188, v159, v188
	v_mul_f32 v192, v159, v192
	v_fma_f32 v188, v164, v189, v188
	v_fma_f32 v192, v164, v193, v192
	v_fma_f32 v188, v165, v190, v188
	v_fma_f32 v192, v165, v194, v192
	v_fma_f32 v188, v167, v191, v188
	v_fma_f32 v192, v167, v195, v192
	v_mul_f32 v196, v159, v196
	v_add_f32_dpp v188, v188, v188 row_half_mirror row_mask:0xf bank_mask:0x5
	v_add_f32_dpp v188, v192, v192 row_half_mirror row_mask:0xf bank_mask:0xa
	v_mul_f32 v197, v164, v197
	v_mul_f32 v198, v165, v198
	v_add_f32_dpp v188, v188, v188 quad_perm:[1,0,3,2] row_mask:0xf bank_mask:0xf
	v_mul_f32 v199, v167, v199
	v_fma_f32 v196, v208, v204, v196
	v_add_f32_dpp v188, v188, v188 quad_perm:[2,3,0,1] row_mask:0xf bank_mask:0xf
	v_fma_f32 v197, v208, v205, v197
	v_fma_f32 v198, v208, v206, v198
	v_add_f32_dpp v188, v188, v188 row_ror:8 row_mask:0xf bank_mask:0xf
	v_fma_f32 v199, v208, v207, v199
	v_fma_f32 v192, v208, v210, v188
	v_mov_b32_dpp v188, v188 row_half_mirror row_mask:0xf bank_mask:0xa
	ds_read_b128 v[204:207], v3 offset:14848
	v_fma_f32 v159, -v188, v200, v196
	v_fma_f32 v164, -v188, v201, v197
	v_fma_f32 v165, -v188, v202, v198
	v_fma_f32 v167, -v188, v203, v199
	v_fma_f32 v192, -v188, v209, v192
	ds_read_b128 v[188:191], v3 offset:13824
	ds_write_b32 v2, v192 offset:448
	ds_read_b128 v[192:195], v3 offset:14080
	ds_read_b128 v[196:199], v3 offset:14336
	ds_read_b128 v[208:211], v4 offset:13824
	ds_read_b128 v[200:203], v3 offset:14592
	s_waitcnt lgkmcnt(7)
	v_mul_f32 v160, v159, v160
	v_mul_f32 v168, v159, v168
	v_fma_f32 v160, v164, v161, v160
	v_fma_f32 v168, v164, v169, v168
	v_fma_f32 v160, v165, v162, v160
	v_fma_f32 v168, v165, v170, v168
	v_fma_f32 v160, v167, v163, v160
	v_fma_f32 v168, v167, v171, v168
	v_mul_f32 v172, v159, v172
	v_add_f32_dpp v160, v160, v160 row_half_mirror row_mask:0xf bank_mask:0x5
	v_add_f32_dpp v160, v168, v168 row_half_mirror row_mask:0xf bank_mask:0xa
	v_mul_f32 v173, v164, v173
	v_mul_f32 v174, v165, v174
	v_add_f32_dpp v160, v160, v160 quad_perm:[1,0,3,2] row_mask:0xf bank_mask:0xf
	v_mul_f32 v175, v167, v175
	v_fma_f32 v172, v184, v180, v172
	v_add_f32_dpp v160, v160, v160 quad_perm:[2,3,0,1] row_mask:0xf bank_mask:0xf
	v_fma_f32 v173, v184, v181, v173
	v_fma_f32 v174, v184, v182, v174
	v_add_f32_dpp v160, v160, v160 row_ror:8 row_mask:0xf bank_mask:0xf
	v_fma_f32 v175, v184, v183, v175
	v_fma_f32 v168, v184, v186, v160
	v_mov_b32_dpp v160, v160 row_half_mirror row_mask:0xf bank_mask:0xa
	ds_read_b128 v[180:183], v3 offset:16384
	v_fma_f32 v159, -v160, v176, v172
	v_fma_f32 v164, -v160, v177, v173
	v_fma_f32 v165, -v160, v178, v174
	v_fma_f32 v167, -v160, v179, v175
	v_fma_f32 v168, -v160, v185, v168
	ds_read_b128 v[160:163], v3 offset:15360
	ds_write_b32 v2, v168 offset:512
	ds_read_b128 v[168:171], v3 offset:15616
	ds_read_b128 v[172:175], v3 offset:15872
	ds_read_b128 v[184:187], v4 offset:15360
	ds_read_b128 v[176:179], v3 offset:16128
	s_waitcnt lgkmcnt(7)
	v_mul_f32 v188, v159, v188
	v_mul_f32 v192, v159, v192
	v_fma_f32 v188, v164, v189, v188
	v_fma_f32 v192, v164, v193, v192
	v_fma_f32 v188, v165, v190, v188
	v_fma_f32 v192, v165, v194, v192
	v_fma_f32 v188, v167, v191, v188
	v_fma_f32 v192, v167, v195, v192
	v_mul_f32 v196, v159, v196
	v_add_f32_dpp v188, v188, v188 row_half_mirror row_mask:0xf bank_mask:0x5
	v_add_f32_dpp v188, v192, v192 row_half_mirror row_mask:0xf bank_mask:0xa
	v_mul_f32 v197, v164, v197
	v_mul_f32 v198, v165, v198
	v_add_f32_dpp v188, v188, v188 quad_perm:[1,0,3,2] row_mask:0xf bank_mask:0xf
	v_mul_f32 v199, v167, v199
	v_fma_f32 v196, v208, v204, v196
	v_add_f32_dpp v188, v188, v188 quad_perm:[2,3,0,1] row_mask:0xf bank_mask:0xf
	v_fma_f32 v197, v208, v205, v197
	v_fma_f32 v198, v208, v206, v198
	v_add_f32_dpp v188, v188, v188 row_ror:8 row_mask:0xf bank_mask:0xf
	v_fma_f32 v199, v208, v207, v199
	v_fma_f32 v192, v208, v210, v188
	v_mov_b32_dpp v188, v188 row_half_mirror row_mask:0xf bank_mask:0xa
	ds_read_b128 v[204:207], v3 offset:17920
	v_fma_f32 v159, -v188, v200, v196
	v_fma_f32 v164, -v188, v201, v197
	v_fma_f32 v165, -v188, v202, v198
	v_fma_f32 v167, -v188, v203, v199
	v_fma_f32 v192, -v188, v209, v192
	ds_read_b128 v[188:191], v3 offset:16896
	ds_write_b32 v2, v192 offset:576
	ds_read_b128 v[192:195], v3 offset:17152
	ds_read_b128 v[196:199], v3 offset:17408
	ds_read_b128 v[208:211], v4 offset:16896
	ds_read_b128 v[200:203], v3 offset:17664
	s_waitcnt lgkmcnt(7)
	v_mul_f32 v160, v159, v160
	v_mul_f32 v168, v159, v168
	v_fma_f32 v160, v164, v161, v160
	v_fma_f32 v168, v164, v169, v168
	v_fma_f32 v160, v165, v162, v160
	v_fma_f32 v168, v165, v170, v168
	v_fma_f32 v160, v167, v163, v160
	v_fma_f32 v168, v167, v171, v168
	v_mul_f32 v172, v159, v172
	v_add_f32_dpp v160, v160, v160 row_half_mirror row_mask:0xf bank_mask:0x5
	v_add_f32_dpp v160, v168, v168 row_half_mirror row_mask:0xf bank_mask:0xa
	v_mul_f32 v173, v164, v173
	v_mul_f32 v174, v165, v174
	v_add_f32_dpp v160, v160, v160 quad_perm:[1,0,3,2] row_mask:0xf bank_mask:0xf
	v_mul_f32 v175, v167, v175
	v_fma_f32 v172, v184, v180, v172
	v_add_f32_dpp v160, v160, v160 quad_perm:[2,3,0,1] row_mask:0xf bank_mask:0xf
	v_fma_f32 v173, v184, v181, v173
	v_fma_f32 v174, v184, v182, v174
	v_add_f32_dpp v160, v160, v160 row_ror:8 row_mask:0xf bank_mask:0xf
	v_fma_f32 v175, v184, v183, v175
	v_fma_f32 v168, v184, v186, v160
	v_mov_b32_dpp v160, v160 row_half_mirror row_mask:0xf bank_mask:0xa
	ds_read_b128 v[180:183], v3 offset:19456
	v_fma_f32 v159, -v160, v176, v172
	v_fma_f32 v164, -v160, v177, v173
	v_fma_f32 v165, -v160, v178, v174
	v_fma_f32 v167, -v160, v179, v175
	v_fma_f32 v168, -v160, v185, v168
	ds_read_b128 v[160:163], v3 offset:18432
	ds_write_b32 v2, v168 offset:640
	ds_read_b128 v[168:171], v3 offset:18688
	ds_read_b128 v[172:175], v3 offset:18944
	ds_read_b128 v[184:187], v4 offset:18432
	ds_read_b128 v[176:179], v3 offset:19200
	s_waitcnt lgkmcnt(7)
; __device__ __forceinline__ float vfma(float a, float b, float c) { float d; asm("v_fma_f32 %0, %1, %2, %3" : "=v"(d) : "v"(a), "v"(b), "v"(c)); return d; }
; __device__ __forceinline__ float vnfma(float a, float b, float c) { float d; asm("v_fma_f32 %0, -%1, %2, %3" : "=v"(d) : "v"(a), "v"(b), "v"(c)); return d; }
; __device__ __forceinline__ float vmul(float a, float b) { float d; asm("v_mul_f32 %0, %1, %2" : "=v"(d) : "v"(a), "v"(b)); return d; }
; __device__ __forceinline__ float vadd(float a, float b) { float d; asm("v_add_f32 %0, %1, %2" : "=v"(d) : "v"(a), "v"(b)); return d; }
; __device__ __forceinline__ float step_compute(float (&S)[4], const StepOp& o) {
;     float d1 = vmul(S[0], o.kk[0]), d2 = vmul(S[0], o.wr[0]), e1 = vmul(S[1], o.kk[1]), e2 = vmul(S[1], o.wr[1]);
;     d1 = vfma(S[2], o.kk[2], d1); d2 = vfma(S[2], o.wr[2], d2); e1 = vfma(S[3], o.kk[3], e1); e2 = vfma(S[3], o.wr[3], e2);
;     d1 = vadd(d1, e1); d2 = vadd(d2, e2);
;     float t0, t1, t2, t3;
;     asm volatile(
;         "v_mul_f32 %[t0], %[s0], %[w0]\n\t"
;         "v_mul_f32 %[t1], %[s1], %[w1]\n\t"
;         "v_add_f32_dpp %[d1], %[d1], %[d1] quad_perm:[1,0,3,2] row_mask:0xf bank_mask:0xf bound_ctrl:1\n\t"
;         "v_add_f32_dpp %[d2], %[d2], %[d2] quad_perm:[1,0,3,2] row_mask:0xf bank_mask:0xf bound_ctrl:1\n\t"
;         "v_mul_f32 %[t2], %[s2], %[w2]\n\t"
;         "v_add_f32_dpp %[d1], %[d1], %[d1] quad_perm:[2,3,0,1] row_mask:0xf bank_mask:0xf bound_ctrl:1\n\t"
;         "v_add_f32_dpp %[d2], %[d2], %[d2] quad_perm:[2,3,0,1] row_mask:0xf bank_mask:0xf bound_ctrl:1\n\t"
;         "v_mul_f32 %[t3], %[s3], %[w3]\n\t"
;         "v_add_f32_dpp %[d1], %[d1], %[d1] row_half_mirror row_mask:0xf bank_mask:0xf bound_ctrl:1\n\t"
;         "v_add_f32_dpp %[d2], %[d2], %[d2] row_half_mirror row_mask:0xf bank_mask:0xf bound_ctrl:1\n\t"
;         "v_fma_f32 %[t0], %[v], %[k0], %[t0]\n\t"
;         "v_add_f32_dpp %[d1], %[d1], %[d1] row_mirror row_mask:0xf bank_mask:0xf bound_ctrl:1\n\t"
;         "v_add_f32_dpp %[d2], %[d2], %[d2] row_mirror row_mask:0xf bank_mask:0xf bound_ctrl:1\n\t"
;         "v_fma_f32 %[t1], %[v], %[k1], %[t1]\n\t"
;         "v_fma_f32 %[t2], %[v], %[k2], %[t2]\n\t"
;         "v_fma_f32 %[t3], %[v], %[k3], %[t3]"
;         : [t0] "=&v"(t0), [t1] "=&v"(t1), [t2] "=&v"(t2), [t3] "=&v"(t3), [d1] "+v"(d1), [d2] "+v"(d2)
	v_mul_f32 v188, v159, v188
	v_mul_f32 v192, v159, v192
	v_fma_f32 v188, v164, v189, v188
	v_fma_f32 v192, v164, v193, v192
	v_fma_f32 v188, v165, v190, v188
	v_fma_f32 v192, v165, v194, v192
	v_fma_f32 v188, v167, v191, v188
	v_fma_f32 v192, v167, v195, v192
	v_mul_f32 v196, v159, v196
	v_add_f32_dpp v188, v188, v188 row_half_mirror row_mask:0xf bank_mask:0x5
	v_add_f32_dpp v188, v192, v192 row_half_mirror row_mask:0xf bank_mask:0xa
	v_mul_f32 v197, v164, v197
	v_mul_f32 v198, v165, v198
	v_add_f32_dpp v188, v188, v188 quad_perm:[1,0,3,2] row_mask:0xf bank_mask:0xf
	v_mul_f32 v199, v167, v199
	v_fma_f32 v196, v208, v204, v196
	v_add_f32_dpp v188, v188, v188 quad_perm:[2,3,0,1] row_mask:0xf bank_mask:0xf
	v_fma_f32 v197, v208, v205, v197
	v_fma_f32 v198, v208, v206, v198
	v_add_f32_dpp v188, v188, v188 row_ror:8 row_mask:0xf bank_mask:0xf
	v_fma_f32 v199, v208, v207, v199
	v_fma_f32 v192, v208, v210, v188
	v_mov_b32_dpp v188, v188 row_half_mirror row_mask:0xf bank_mask:0xa
	ds_read_b128 v[204:207], v3 offset:20992
	v_fma_f32 v159, -v188, v200, v196
	v_fma_f32 v164, -v188, v201, v197
	v_fma_f32 v165, -v188, v202, v198
	v_fma_f32 v167, -v188, v203, v199
	v_fma_f32 v192, -v188, v209, v192
	ds_read_b128 v[188:191], v3 offset:19968
	ds_write_b32 v2, v192 offset:704
	ds_read_b128 v[192:195], v3 offset:20224
	ds_read_b128 v[196:199], v3 offset:20480
	ds_read_b128 v[208:211], v4 offset:19968
	ds_read_b128 v[200:203], v3 offset:20736
	s_waitcnt lgkmcnt(7)
	v_mul_f32 v160, v159, v160
	v_mul_f32 v168, v159, v168
	v_fma_f32 v160, v164, v161, v160
	v_fma_f32 v168, v164, v169, v168
	v_fma_f32 v160, v165, v162, v160
	v_fma_f32 v168, v165, v170, v168
	v_fma_f32 v160, v167, v163, v160
	v_fma_f32 v168, v167, v171, v168
	v_mul_f32 v172, v159, v172
	v_add_f32_dpp v160, v160, v160 row_half_mirror row_mask:0xf bank_mask:0x5
	v_add_f32_dpp v160, v168, v168 row_half_mirror row_mask:0xf bank_mask:0xa
	v_mul_f32 v173, v164, v173
	v_mul_f32 v174, v165, v174
	v_add_f32_dpp v160, v160, v160 quad_perm:[1,0,3,2] row_mask:0xf bank_mask:0xf
	v_mul_f32 v175, v167, v175
	v_fma_f32 v172, v184, v180, v172
	v_add_f32_dpp v160, v160, v160 quad_perm:[2,3,0,1] row_mask:0xf bank_mask:0xf
	v_fma_f32 v173, v184, v181, v173
	v_fma_f32 v174, v184, v182, v174
	v_add_f32_dpp v160, v160, v160 row_ror:8 row_mask:0xf bank_mask:0xf
	v_fma_f32 v175, v184, v183, v175
	v_fma_f32 v168, v184, v186, v160
	v_mov_b32_dpp v160, v160 row_half_mirror row_mask:0xf bank_mask:0xa
	ds_read_b128 v[180:183], v3 offset:22528
	v_fma_f32 v159, -v160, v176, v172
	v_fma_f32 v164, -v160, v177, v173
	v_fma_f32 v165, -v160, v178, v174
	v_fma_f32 v167, -v160, v179, v175
	v_fma_f32 v168, -v160, v185, v168
	ds_read_b128 v[160:163], v3 offset:21504
	ds_write_b32 v2, v168 offset:768
	ds_read_b128 v[168:171], v3 offset:21760
	ds_read_b128 v[172:175], v3 offset:22016
	ds_read_b128 v[184:187], v4 offset:21504
	ds_read_b128 v[176:179], v3 offset:22272
	s_waitcnt lgkmcnt(7)
	v_mul_f32 v188, v159, v188
	v_mul_f32 v192, v159, v192
	v_fma_f32 v188, v164, v189, v188
	v_fma_f32 v192, v164, v193, v192
	v_fma_f32 v188, v165, v190, v188
	v_fma_f32 v192, v165, v194, v192
	v_fma_f32 v188, v167, v191, v188
	v_fma_f32 v192, v167, v195, v192
	v_mul_f32 v196, v159, v196
	v_add_f32_dpp v188, v188, v188 row_half_mirror row_mask:0xf bank_mask:0x5
	v_add_f32_dpp v188, v192, v192 row_half_mirror row_mask:0xf bank_mask:0xa
	v_mul_f32 v197, v164, v197
	v_mul_f32 v198, v165, v198
	v_add_f32_dpp v188, v188, v188 quad_perm:[1,0,3,2] row_mask:0xf bank_mask:0xf
	v_mul_f32 v199, v167, v199
	v_fma_f32 v196, v208, v204, v196
	v_add_f32_dpp v188, v188, v188 quad_perm:[2,3,0,1] row_mask:0xf bank_mask:0xf
	v_fma_f32 v197, v208, v205, v197
	v_fma_f32 v198, v208, v206, v198
	v_add_f32_dpp v188, v188, v188 row_ror:8 row_mask:0xf bank_mask:0xf
	v_fma_f32 v199, v208, v207, v199
	v_fma_f32 v192, v208, v210, v188
	v_mov_b32_dpp v188, v188 row_half_mirror row_mask:0xf bank_mask:0xa
	ds_read_b128 v[204:207], v3 offset:24064
	v_fma_f32 v159, -v188, v200, v196
	v_fma_f32 v164, -v188, v201, v197
	v_fma_f32 v165, -v188, v202, v198
	v_fma_f32 v167, -v188, v203, v199
	v_fma_f32 v192, -v188, v209, v192
	ds_read_b128 v[188:191], v3 offset:23040
	ds_write_b32 v2, v192 offset:832
	ds_read_b128 v[192:195], v3 offset:23296
	ds_read_b128 v[196:199], v3 offset:23552
	ds_read_b128 v[208:211], v4 offset:23040
	ds_read_b128 v[200:203], v3 offset:23808
	s_waitcnt lgkmcnt(7)
	v_mul_f32 v160, v159, v160
	v_mul_f32 v168, v159, v168
	v_fma_f32 v160, v164, v161, v160
	v_fma_f32 v168, v164, v169, v168
	v_fma_f32 v160, v165, v162, v160
	v_fma_f32 v168, v165, v170, v168
	v_fma_f32 v160, v167, v163, v160
	v_fma_f32 v168, v167, v171, v168
	v_mul_f32 v172, v159, v172
	v_add_f32_dpp v160, v160, v160 row_half_mirror row_mask:0xf bank_mask:0x5
	v_add_f32_dpp v160, v168, v168 row_half_mirror row_mask:0xf bank_mask:0xa
	v_mul_f32 v173, v164, v173
	v_mul_f32 v174, v165, v174
	v_add_f32_dpp v160, v160, v160 quad_perm:[1,0,3,2] row_mask:0xf bank_mask:0xf
	v_mul_f32 v175, v167, v175
	v_fma_f32 v172, v184, v180, v172
	v_add_f32_dpp v160, v160, v160 quad_perm:[2,3,0,1] row_mask:0xf bank_mask:0xf
	v_fma_f32 v173, v184, v181, v173
	v_fma_f32 v174, v184, v182, v174
	v_add_f32_dpp v160, v160, v160 row_ror:8 row_mask:0xf bank_mask:0xf
	v_fma_f32 v175, v184, v183, v175
	v_fma_f32 v168, v184, v186, v160
	v_mov_b32_dpp v160, v160 row_half_mirror row_mask:0xf bank_mask:0xa
	ds_read_b128 v[180:183], v3 offset:25600
	v_fma_f32 v159, -v160, v176, v172
	v_fma_f32 v164, -v160, v177, v173
	v_fma_f32 v165, -v160, v178, v174
	v_fma_f32 v167, -v160, v179, v175
	v_fma_f32 v168, -v160, v185, v168
	ds_read_b128 v[160:163], v3 offset:24576
	ds_write_b32 v2, v168 offset:896
	ds_read_b128 v[168:171], v3 offset:24832
	ds_read_b128 v[172:175], v3 offset:25088
	ds_read_b128 v[184:187], v4 offset:24576
	ds_read_b128 v[176:179], v3 offset:25344
	s_waitcnt lgkmcnt(7)
; __device__ __forceinline__ float vfma(float a, float b, float c) { float d; asm("v_fma_f32 %0, %1, %2, %3" : "=v"(d) : "v"(a), "v"(b), "v"(c)); return d; }
; __device__ __forceinline__ float vnfma(float a, float b, float c) { float d; asm("v_fma_f32 %0, -%1, %2, %3" : "=v"(d) : "v"(a), "v"(b), "v"(c)); return d; }
; __device__ __forceinline__ float vmul(float a, float b) { float d; asm("v_mul_f32 %0, %1, %2" : "=v"(d) : "v"(a), "v"(b)); return d; }
; __device__ __forceinline__ float vadd(float a, float b) { float d; asm("v_add_f32 %0, %1, %2" : "=v"(d) : "v"(a), "v"(b)); return d; }
; __device__ __forceinline__ float step_compute(float (&S)[4], const StepOp& o) {
;     float d1 = vmul(S[0], o.kk[0]), d2 = vmul(S[0], o.wr[0]), e1 = vmul(S[1], o.kk[1]), e2 = vmul(S[1], o.wr[1]);
;     d1 = vfma(S[2], o.kk[2], d1); d2 = vfma(S[2], o.wr[2], d2); e1 = vfma(S[3], o.kk[3], e1); e2 = vfma(S[3], o.wr[3], e2);
;     d1 = vadd(d1, e1); d2 = vadd(d2, e2);
;     float t0, t1, t2, t3;
;     asm volatile(
;         "v_mul_f32 %[t0], %[s0], %[w0]\n\t"
;         "v_mul_f32 %[t1], %[s1], %[w1]\n\t"
;         "v_add_f32_dpp %[d1], %[d1], %[d1] quad_perm:[1,0,3,2] row_mask:0xf bank_mask:0xf bound_ctrl:1\n\t"
;         "v_add_f32_dpp %[d2], %[d2], %[d2] quad_perm:[1,0,3,2] row_mask:0xf bank_mask:0xf bound_ctrl:1\n\t"
;         "v_mul_f32 %[t2], %[s2], %[w2]\n\t"
;         "v_add_f32_dpp %[d1], %[d1], %[d1] quad_perm:[2,3,0,1] row_mask:0xf bank_mask:0xf bound_ctrl:1\n\t"
;         "v_add_f32_dpp %[d2], %[d2], %[d2] quad_perm:[2,3,0,1] row_mask:0xf bank_mask:0xf bound_ctrl:1\n\t"
;         "v_mul_f32 %[t3], %[s3], %[w3]\n\t"
;         "v_add_f32_dpp %[d1], %[d1], %[d1] row_half_mirror row_mask:0xf bank_mask:0xf bound_ctrl:1\n\t"
;         "v_add_f32_dpp %[d2], %[d2], %[d2] row_half_mirror row_mask:0xf bank_mask:0xf bound_ctrl:1\n\t"
;         "v_fma_f32 %[t0], %[v], %[k0], %[t0]\n\t"
;         "v_add_f32_dpp %[d1], %[d1], %[d1] row_mirror row_mask:0xf bank_mask:0xf bound_ctrl:1\n\t"
;         "v_add_f32_dpp %[d2], %[d2], %[d2] row_mirror row_mask:0xf bank_mask:0xf bound_ctrl:1\n\t"
;         "v_fma_f32 %[t1], %[v], %[k1], %[t1]\n\t"
;         "v_fma_f32 %[t2], %[v], %[k2], %[t2]\n\t"
;         "v_fma_f32 %[t3], %[v], %[k3], %[t3]"
;         : [t0] "=&v"(t0), [t1] "=&v"(t1), [t2] "=&v"(t2), [t3] "=&v"(t3), [d1] "+v"(d1), [d2] "+v"(d2)
	v_mul_f32 v188, v159, v188
	v_mul_f32 v192, v159, v192
	v_fma_f32 v188, v164, v189, v188
	v_fma_f32 v192, v164, v193, v192
	v_fma_f32 v188, v165, v190, v188
	v_fma_f32 v192, v165, v194, v192
	v_fma_f32 v188, v167, v191, v188
	v_fma_f32 v192, v167, v195, v192
	v_mul_f32 v196, v159, v196
	v_add_f32_dpp v188, v188, v188 row_half_mirror row_mask:0xf bank_mask:0x5
	v_add_f32_dpp v188, v192, v192 row_half_mirror row_mask:0xf bank_mask:0xa
	v_mul_f32 v197, v164, v197
	v_mul_f32 v198, v165, v198
	v_add_f32_dpp v188, v188, v188 quad_perm:[1,0,3,2] row_mask:0xf bank_mask:0xf
	v_mul_f32 v199, v167, v199
	v_fma_f32 v196, v208, v204, v196
	v_add_f32_dpp v188, v188, v188 quad_perm:[2,3,0,1] row_mask:0xf bank_mask:0xf
	v_fma_f32 v197, v208, v205, v197
	v_fma_f32 v198, v208, v206, v198
	v_add_f32_dpp v188, v188, v188 row_ror:8 row_mask:0xf bank_mask:0xf
	v_fma_f32 v199, v208, v207, v199
	v_fma_f32 v192, v208, v210, v188
	v_mov_b32_dpp v188, v188 row_half_mirror row_mask:0xf bank_mask:0xa
	ds_read_b128 v[204:207], v3 offset:27136
	v_fma_f32 v159, -v188, v200, v196
	v_fma_f32 v164, -v188, v201, v197
	v_fma_f32 v165, -v188, v202, v198
	v_fma_f32 v167, -v188, v203, v199
	v_fma_f32 v192, -v188, v209, v192
	ds_read_b128 v[188:191], v3 offset:26112
	ds_write_b32 v2, v192 offset:960
	ds_read_b128 v[192:195], v3 offset:26368
	ds_read_b128 v[196:199], v3 offset:26624
	ds_read_b128 v[208:211], v4 offset:26112
	ds_read_b128 v[200:203], v3 offset:26880
	s_waitcnt lgkmcnt(7)
	v_mul_f32 v160, v159, v160
	v_mul_f32 v168, v159, v168
	v_fma_f32 v160, v164, v161, v160
	v_fma_f32 v168, v164, v169, v168
	v_fma_f32 v160, v165, v162, v160
	v_fma_f32 v168, v165, v170, v168
	v_fma_f32 v160, v167, v163, v160
	v_fma_f32 v168, v167, v171, v168
	v_mul_f32 v172, v159, v172
	v_add_f32_dpp v160, v160, v160 row_half_mirror row_mask:0xf bank_mask:0x5
	v_add_f32_dpp v160, v168, v168 row_half_mirror row_mask:0xf bank_mask:0xa
	v_mul_f32 v173, v164, v173
	v_mul_f32 v174, v165, v174
	v_add_f32_dpp v160, v160, v160 quad_perm:[1,0,3,2] row_mask:0xf bank_mask:0xf
	v_mul_f32 v175, v167, v175
	v_fma_f32 v172, v184, v180, v172
	v_add_f32_dpp v160, v160, v160 quad_perm:[2,3,0,1] row_mask:0xf bank_mask:0xf
	v_fma_f32 v173, v184, v181, v173
	v_fma_f32 v174, v184, v182, v174
	v_add_f32_dpp v160, v160, v160 row_ror:8 row_mask:0xf bank_mask:0xf
	v_fma_f32 v175, v184, v183, v175
	v_fma_f32 v168, v184, v186, v160
	v_mov_b32_dpp v160, v160 row_half_mirror row_mask:0xf bank_mask:0xa
	ds_read_b128 v[180:183], v3 offset:28672
	v_fma_f32 v159, -v160, v176, v172
	v_fma_f32 v164, -v160, v177, v173
	v_fma_f32 v165, -v160, v178, v174
	v_fma_f32 v167, -v160, v179, v175
	v_fma_f32 v168, -v160, v185, v168
	ds_read_b128 v[160:163], v3 offset:27648
	ds_write_b32 v2, v168 offset:1024
	ds_read_b128 v[168:171], v3 offset:27904
	ds_read_b128 v[172:175], v3 offset:28160
	ds_read_b128 v[184:187], v4 offset:27648
	ds_read_b128 v[176:179], v3 offset:28416
	s_waitcnt lgkmcnt(7)
	v_mul_f32 v188, v159, v188
	v_mul_f32 v192, v159, v192
	v_fma_f32 v188, v164, v189, v188
	v_fma_f32 v192, v164, v193, v192
	v_fma_f32 v188, v165, v190, v188
	v_fma_f32 v192, v165, v194, v192
	v_fma_f32 v188, v167, v191, v188
	v_fma_f32 v192, v167, v195, v192
	v_mul_f32 v196, v159, v196
	v_add_f32_dpp v188, v188, v188 row_half_mirror row_mask:0xf bank_mask:0x5
	v_add_f32_dpp v188, v192, v192 row_half_mirror row_mask:0xf bank_mask:0xa
	v_mul_f32 v197, v164, v197
	v_mul_f32 v198, v165, v198
	v_add_f32_dpp v188, v188, v188 quad_perm:[1,0,3,2] row_mask:0xf bank_mask:0xf
	v_mul_f32 v199, v167, v199
	v_fma_f32 v196, v208, v204, v196
	v_add_f32_dpp v188, v188, v188 quad_perm:[2,3,0,1] row_mask:0xf bank_mask:0xf
	v_fma_f32 v197, v208, v205, v197
	v_fma_f32 v198, v208, v206, v198
	v_add_f32_dpp v188, v188, v188 row_ror:8 row_mask:0xf bank_mask:0xf
	v_fma_f32 v199, v208, v207, v199
	v_fma_f32 v192, v208, v210, v188
	v_mov_b32_dpp v188, v188 row_half_mirror row_mask:0xf bank_mask:0xa
	ds_read_b128 v[204:207], v3 offset:30208
	v_fma_f32 v159, -v188, v200, v196
	v_fma_f32 v164, -v188, v201, v197
	v_fma_f32 v165, -v188, v202, v198
	v_fma_f32 v167, -v188, v203, v199
	v_fma_f32 v192, -v188, v209, v192
	ds_read_b128 v[188:191], v3 offset:29184
	ds_write_b32 v2, v192 offset:1088
	ds_read_b128 v[192:195], v3 offset:29440
	ds_read_b128 v[196:199], v3 offset:29696
	ds_read_b128 v[208:211], v4 offset:29184
	ds_read_b128 v[200:203], v3 offset:29952
	s_waitcnt lgkmcnt(7)
	v_mul_f32 v160, v159, v160
	v_mul_f32 v168, v159, v168
	v_fma_f32 v160, v164, v161, v160
	v_fma_f32 v168, v164, v169, v168
	v_fma_f32 v160, v165, v162, v160
	v_fma_f32 v168, v165, v170, v168
	v_fma_f32 v160, v167, v163, v160
	v_fma_f32 v168, v167, v171, v168
	v_mul_f32 v172, v159, v172
	v_add_f32_dpp v160, v160, v160 row_half_mirror row_mask:0xf bank_mask:0x5
	v_add_f32_dpp v160, v168, v168 row_half_mirror row_mask:0xf bank_mask:0xa
	v_mul_f32 v173, v164, v173
	v_mul_f32 v174, v165, v174
	v_add_f32_dpp v160, v160, v160 quad_perm:[1,0,3,2] row_mask:0xf bank_mask:0xf
	v_mul_f32 v175, v167, v175
	v_fma_f32 v172, v184, v180, v172
	v_add_f32_dpp v160, v160, v160 quad_perm:[2,3,0,1] row_mask:0xf bank_mask:0xf
	v_fma_f32 v173, v184, v181, v173
	v_fma_f32 v174, v184, v182, v174
	v_add_f32_dpp v160, v160, v160 row_ror:8 row_mask:0xf bank_mask:0xf
	v_fma_f32 v175, v184, v183, v175
	v_fma_f32 v168, v184, v186, v160
	v_mov_b32_dpp v160, v160 row_half_mirror row_mask:0xf bank_mask:0xa
	ds_read_b128 v[180:183], v3 offset:31744
	v_fma_f32 v159, -v160, v176, v172
	v_fma_f32 v164, -v160, v177, v173
	v_fma_f32 v165, -v160, v178, v174
	v_fma_f32 v167, -v160, v179, v175
	v_fma_f32 v168, -v160, v185, v168
	ds_read_b128 v[160:163], v3 offset:30720
	ds_write_b32 v2, v168 offset:1152
	ds_read_b128 v[168:171], v3 offset:30976
	ds_read_b128 v[172:175], v3 offset:31232
	ds_read_b128 v[184:187], v4 offset:30720
	ds_read_b128 v[176:179], v3 offset:31488
	s_waitcnt lgkmcnt(7)
; __device__ __forceinline__ float vfma(float a, float b, float c) { float d; asm("v_fma_f32 %0, %1, %2, %3" : "=v"(d) : "v"(a), "v"(b), "v"(c)); return d; }
; __device__ __forceinline__ float vnfma(float a, float b, float c) { float d; asm("v_fma_f32 %0, -%1, %2, %3" : "=v"(d) : "v"(a), "v"(b), "v"(c)); return d; }
; __device__ __forceinline__ float vmul(float a, float b) { float d; asm("v_mul_f32 %0, %1, %2" : "=v"(d) : "v"(a), "v"(b)); return d; }
; __device__ __forceinline__ float vadd(float a, float b) { float d; asm("v_add_f32 %0, %1, %2" : "=v"(d) : "v"(a), "v"(b)); return d; }
; __device__ __forceinline__ float step_compute(float (&S)[4], const StepOp& o) {
;     float d1 = vmul(S[0], o.kk[0]), d2 = vmul(S[0], o.wr[0]), e1 = vmul(S[1], o.kk[1]), e2 = vmul(S[1], o.wr[1]);
;     d1 = vfma(S[2], o.kk[2], d1); d2 = vfma(S[2], o.wr[2], d2); e1 = vfma(S[3], o.kk[3], e1); e2 = vfma(S[3], o.wr[3], e2);
;     d1 = vadd(d1, e1); d2 = vadd(d2, e2);
;     float t0, t1, t2, t3;
;     asm volatile(
;         "v_mul_f32 %[t0], %[s0], %[w0]\n\t"
;         "v_mul_f32 %[t1], %[s1], %[w1]\n\t"
;         "v_add_f32_dpp %[d1], %[d1], %[d1] quad_perm:[1,0,3,2] row_mask:0xf bank_mask:0xf bound_ctrl:1\n\t"
;         "v_add_f32_dpp %[d2], %[d2], %[d2] quad_perm:[1,0,3,2] row_mask:0xf bank_mask:0xf bound_ctrl:1\n\t"
;         "v_mul_f32 %[t2], %[s2], %[w2]\n\t"
;         "v_add_f32_dpp %[d1], %[d1], %[d1] quad_perm:[2,3,0,1] row_mask:0xf bank_mask:0xf bound_ctrl:1\n\t"
;         "v_add_f32_dpp %[d2], %[d2], %[d2] quad_perm:[2,3,0,1] row_mask:0xf bank_mask:0xf bound_ctrl:1\n\t"
;         "v_mul_f32 %[t3], %[s3], %[w3]\n\t"
;         "v_add_f32_dpp %[d1], %[d1], %[d1] row_half_mirror row_mask:0xf bank_mask:0xf bound_ctrl:1\n\t"
;         "v_add_f32_dpp %[d2], %[d2], %[d2] row_half_mirror row_mask:0xf bank_mask:0xf bound_ctrl:1\n\t"
;         "v_fma_f32 %[t0], %[v], %[k0], %[t0]\n\t"
;         "v_add_f32_dpp %[d1], %[d1], %[d1] row_mirror row_mask:0xf bank_mask:0xf bound_ctrl:1\n\t"
;         "v_add_f32_dpp %[d2], %[d2], %[d2] row_mirror row_mask:0xf bank_mask:0xf bound_ctrl:1\n\t"
;         "v_fma_f32 %[t1], %[v], %[k1], %[t1]\n\t"
;         "v_fma_f32 %[t2], %[v], %[k2], %[t2]\n\t"
;         "v_fma_f32 %[t3], %[v], %[k3], %[t3]"
;         : [t0] "=&v"(t0), [t1] "=&v"(t1), [t2] "=&v"(t2), [t3] "=&v"(t3), [d1] "+v"(d1), [d2] "+v"(d2)
	v_mul_f32 v188, v159, v188
	v_mul_f32 v192, v159, v192
	v_fma_f32 v188, v164, v189, v188
	v_fma_f32 v192, v164, v193, v192
	v_fma_f32 v188, v165, v190, v188
	v_fma_f32 v192, v165, v194, v192
	v_fma_f32 v188, v167, v191, v188
	v_fma_f32 v192, v167, v195, v192
	v_mul_f32 v196, v159, v196
	v_add_f32_dpp v188, v188, v188 row_half_mirror row_mask:0xf bank_mask:0x5
	v_add_f32_dpp v188, v192, v192 row_half_mirror row_mask:0xf bank_mask:0xa
	v_mul_f32 v197, v164, v197
	v_mul_f32 v198, v165, v198
	v_add_f32_dpp v188, v188, v188 quad_perm:[1,0,3,2] row_mask:0xf bank_mask:0xf
	v_mul_f32 v199, v167, v199
	v_fma_f32 v196, v208, v204, v196
	v_add_f32_dpp v188, v188, v188 quad_perm:[2,3,0,1] row_mask:0xf bank_mask:0xf
	v_fma_f32 v197, v208, v205, v197
	v_fma_f32 v198, v208, v206, v198
	v_add_f32_dpp v188, v188, v188 row_ror:8 row_mask:0xf bank_mask:0xf
	v_fma_f32 v199, v208, v207, v199
	v_fma_f32 v192, v208, v210, v188
	v_mov_b32_dpp v188, v188 row_half_mirror row_mask:0xf bank_mask:0xa
	ds_read_b128 v[204:207], v3 offset:33280
	v_fma_f32 v159, -v188, v200, v196
	v_fma_f32 v164, -v188, v201, v197
	v_fma_f32 v165, -v188, v202, v198
	v_fma_f32 v167, -v188, v203, v199
	v_fma_f32 v192, -v188, v209, v192
	ds_read_b128 v[188:191], v3 offset:32256
	ds_write_b32 v2, v192 offset:1216
	ds_read_b128 v[192:195], v3 offset:32512
	ds_read_b128 v[196:199], v3 offset:32768
	ds_read_b128 v[208:211], v4 offset:32256
	ds_read_b128 v[200:203], v3 offset:33024
	s_waitcnt lgkmcnt(7)
	v_mul_f32 v160, v159, v160
	v_mul_f32 v168, v159, v168
	v_fma_f32 v160, v164, v161, v160
	v_fma_f32 v168, v164, v169, v168
	v_fma_f32 v160, v165, v162, v160
	v_fma_f32 v168, v165, v170, v168
	v_fma_f32 v160, v167, v163, v160
	v_fma_f32 v168, v167, v171, v168
	v_mul_f32 v172, v159, v172
	v_add_f32_dpp v160, v160, v160 row_half_mirror row_mask:0xf bank_mask:0x5
	v_add_f32_dpp v160, v168, v168 row_half_mirror row_mask:0xf bank_mask:0xa
	v_mul_f32 v173, v164, v173
	v_mul_f32 v174, v165, v174
	v_add_f32_dpp v160, v160, v160 quad_perm:[1,0,3,2] row_mask:0xf bank_mask:0xf
	v_mul_f32 v175, v167, v175
	v_fma_f32 v172, v184, v180, v172
	v_add_f32_dpp v160, v160, v160 quad_perm:[2,3,0,1] row_mask:0xf bank_mask:0xf
	v_fma_f32 v173, v184, v181, v173
	v_fma_f32 v174, v184, v182, v174
	v_add_f32_dpp v160, v160, v160 row_ror:8 row_mask:0xf bank_mask:0xf
	v_fma_f32 v175, v184, v183, v175
	v_fma_f32 v168, v184, v186, v160
	v_mov_b32_dpp v160, v160 row_half_mirror row_mask:0xf bank_mask:0xa
	ds_read_b128 v[180:183], v3 offset:34816
	v_fma_f32 v159, -v160, v176, v172
	v_fma_f32 v164, -v160, v177, v173
	v_fma_f32 v165, -v160, v178, v174
	v_fma_f32 v167, -v160, v179, v175
	v_fma_f32 v168, -v160, v185, v168
	ds_read_b128 v[160:163], v3 offset:33792
	ds_write_b32 v2, v168 offset:1280
	ds_read_b128 v[168:171], v3 offset:34048
	ds_read_b128 v[172:175], v3 offset:34304
	ds_read_b128 v[184:187], v4 offset:33792
	ds_read_b128 v[176:179], v3 offset:34560
	s_waitcnt lgkmcnt(7)
	v_mul_f32 v188, v159, v188
	v_mul_f32 v192, v159, v192
	v_fma_f32 v188, v164, v189, v188
	v_fma_f32 v192, v164, v193, v192
	v_fma_f32 v188, v165, v190, v188
	v_fma_f32 v192, v165, v194, v192
	v_fma_f32 v188, v167, v191, v188
	v_fma_f32 v192, v167, v195, v192
	v_mul_f32 v196, v159, v196
	v_add_f32_dpp v188, v188, v188 row_half_mirror row_mask:0xf bank_mask:0x5
	v_add_f32_dpp v188, v192, v192 row_half_mirror row_mask:0xf bank_mask:0xa
	v_mul_f32 v197, v164, v197
	v_mul_f32 v198, v165, v198
	v_add_f32_dpp v188, v188, v188 quad_perm:[1,0,3,2] row_mask:0xf bank_mask:0xf
	v_mul_f32 v199, v167, v199
	v_fma_f32 v196, v208, v204, v196
	v_add_f32_dpp v188, v188, v188 quad_perm:[2,3,0,1] row_mask:0xf bank_mask:0xf
	v_fma_f32 v197, v208, v205, v197
	v_fma_f32 v198, v208, v206, v198
	v_add_f32_dpp v188, v188, v188 row_ror:8 row_mask:0xf bank_mask:0xf
	v_fma_f32 v199, v208, v207, v199
	v_fma_f32 v192, v208, v210, v188
	v_mov_b32_dpp v188, v188 row_half_mirror row_mask:0xf bank_mask:0xa
	ds_read_b128 v[204:207], v3 offset:36352
	v_fma_f32 v159, -v188, v200, v196
	v_fma_f32 v164, -v188, v201, v197
	v_fma_f32 v165, -v188, v202, v198
	v_fma_f32 v167, -v188, v203, v199
	v_fma_f32 v192, -v188, v209, v192
	ds_read_b128 v[188:191], v3 offset:35328
	ds_write_b32 v2, v192 offset:1344
	ds_read_b128 v[192:195], v3 offset:35584
	ds_read_b128 v[196:199], v3 offset:35840
	ds_read_b128 v[208:211], v4 offset:35328
	ds_read_b128 v[200:203], v3 offset:36096
	s_waitcnt lgkmcnt(7)
	v_mul_f32 v160, v159, v160
	v_mul_f32 v168, v159, v168
	v_fma_f32 v160, v164, v161, v160
	v_fma_f32 v168, v164, v169, v168
	v_fma_f32 v160, v165, v162, v160
	v_fma_f32 v168, v165, v170, v168
	v_fma_f32 v160, v167, v163, v160
	v_fma_f32 v168, v167, v171, v168
	v_mul_f32 v172, v159, v172
	v_add_f32_dpp v160, v160, v160 row_half_mirror row_mask:0xf bank_mask:0x5
	v_add_f32_dpp v160, v168, v168 row_half_mirror row_mask:0xf bank_mask:0xa
	v_mul_f32 v173, v164, v173
	v_mul_f32 v174, v165, v174
	v_add_f32_dpp v160, v160, v160 quad_perm:[1,0,3,2] row_mask:0xf bank_mask:0xf
	v_mul_f32 v175, v167, v175
	v_fma_f32 v172, v184, v180, v172
	v_add_f32_dpp v160, v160, v160 quad_perm:[2,3,0,1] row_mask:0xf bank_mask:0xf
	v_fma_f32 v173, v184, v181, v173
	v_fma_f32 v174, v184, v182, v174
	v_add_f32_dpp v160, v160, v160 row_ror:8 row_mask:0xf bank_mask:0xf
	v_fma_f32 v175, v184, v183, v175
	v_fma_f32 v168, v184, v186, v160
	v_mov_b32_dpp v160, v160 row_half_mirror row_mask:0xf bank_mask:0xa
	ds_read_b128 v[180:183], v3 offset:37888
	v_fma_f32 v159, -v160, v176, v172
	v_fma_f32 v164, -v160, v177, v173
	v_fma_f32 v165, -v160, v178, v174
	v_fma_f32 v167, -v160, v179, v175
	v_fma_f32 v168, -v160, v185, v168
	ds_read_b128 v[160:163], v3 offset:36864
	ds_write_b32 v2, v168 offset:1408
	ds_read_b128 v[168:171], v3 offset:37120
	ds_read_b128 v[172:175], v3 offset:37376
	ds_read_b128 v[184:187], v4 offset:36864
	ds_read_b128 v[176:179], v3 offset:37632
	s_waitcnt lgkmcnt(7)
; __device__ __forceinline__ float vfma(float a, float b, float c) { float d; asm("v_fma_f32 %0, %1, %2, %3" : "=v"(d) : "v"(a), "v"(b), "v"(c)); return d; }
; __device__ __forceinline__ float vnfma(float a, float b, float c) { float d; asm("v_fma_f32 %0, -%1, %2, %3" : "=v"(d) : "v"(a), "v"(b), "v"(c)); return d; }
; __device__ __forceinline__ float vmul(float a, float b) { float d; asm("v_mul_f32 %0, %1, %2" : "=v"(d) : "v"(a), "v"(b)); return d; }
; __device__ __forceinline__ float vadd(float a, float b) { float d; asm("v_add_f32 %0, %1, %2" : "=v"(d) : "v"(a), "v"(b)); return d; }
; __device__ __forceinline__ float step_compute(float (&S)[4], const StepOp& o) {
;     float d1 = vmul(S[0], o.kk[0]), d2 = vmul(S[0], o.wr[0]), e1 = vmul(S[1], o.kk[1]), e2 = vmul(S[1], o.wr[1]);
;     d1 = vfma(S[2], o.kk[2], d1); d2 = vfma(S[2], o.wr[2], d2); e1 = vfma(S[3], o.kk[3], e1); e2 = vfma(S[3], o.wr[3], e2);
;     d1 = vadd(d1, e1); d2 = vadd(d2, e2);
;     float t0, t1, t2, t3;
;     asm volatile(
;         "v_mul_f32 %[t0], %[s0], %[w0]\n\t"
;         "v_mul_f32 %[t1], %[s1], %[w1]\n\t"
;         "v_add_f32_dpp %[d1], %[d1], %[d1] quad_perm:[1,0,3,2] row_mask:0xf bank_mask:0xf bound_ctrl:1\n\t"
;         "v_add_f32_dpp %[d2], %[d2], %[d2] quad_perm:[1,0,3,2] row_mask:0xf bank_mask:0xf bound_ctrl:1\n\t"
;         "v_mul_f32 %[t2], %[s2], %[w2]\n\t"
;         "v_add_f32_dpp %[d1], %[d1], %[d1] quad_perm:[2,3,0,1] row_mask:0xf bank_mask:0xf bound_ctrl:1\n\t"
;         "v_add_f32_dpp %[d2], %[d2], %[d2] quad_perm:[2,3,0,1] row_mask:0xf bank_mask:0xf bound_ctrl:1\n\t"
;         "v_mul_f32 %[t3], %[s3], %[w3]\n\t"
;         "v_add_f32_dpp %[d1], %[d1], %[d1] row_half_mirror row_mask:0xf bank_mask:0xf bound_ctrl:1\n\t"
;         "v_add_f32_dpp %[d2], %[d2], %[d2] row_half_mirror row_mask:0xf bank_mask:0xf bound_ctrl:1\n\t"
;         "v_fma_f32 %[t0], %[v], %[k0], %[t0]\n\t"
;         "v_add_f32_dpp %[d1], %[d1], %[d1] row_mirror row_mask:0xf bank_mask:0xf bound_ctrl:1\n\t"
;         "v_add_f32_dpp %[d2], %[d2], %[d2] row_mirror row_mask:0xf bank_mask:0xf bound_ctrl:1\n\t"
;         "v_fma_f32 %[t1], %[v], %[k1], %[t1]\n\t"
;         "v_fma_f32 %[t2], %[v], %[k2], %[t2]\n\t"
;         "v_fma_f32 %[t3], %[v], %[k3], %[t3]"
;         : [t0] "=&v"(t0), [t1] "=&v"(t1), [t2] "=&v"(t2), [t3] "=&v"(t3), [d1] "+v"(d1), [d2] "+v"(d2)
	v_mul_f32 v188, v159, v188
	v_mul_f32 v192, v159, v192
	v_fma_f32 v188, v164, v189, v188
	v_fma_f32 v192, v164, v193, v192
	v_fma_f32 v188, v165, v190, v188
	v_fma_f32 v192, v165, v194, v192
	v_fma_f32 v188, v167, v191, v188
	v_fma_f32 v192, v167, v195, v192
	v_mul_f32 v196, v159, v196
	v_add_f32_dpp v188, v188, v188 row_half_mirror row_mask:0xf bank_mask:0x5
	v_add_f32_dpp v188, v192, v192 row_half_mirror row_mask:0xf bank_mask:0xa
	v_mul_f32 v197, v164, v197
	v_mul_f32 v198, v165, v198
	v_add_f32_dpp v188, v188, v188 quad_perm:[1,0,3,2] row_mask:0xf bank_mask:0xf
	v_mul_f32 v199, v167, v199
	v_fma_f32 v196, v208, v204, v196
	v_add_f32_dpp v188, v188, v188 quad_perm:[2,3,0,1] row_mask:0xf bank_mask:0xf
	v_fma_f32 v197, v208, v205, v197
	v_fma_f32 v198, v208, v206, v198
	v_add_f32_dpp v188, v188, v188 row_ror:8 row_mask:0xf bank_mask:0xf
	v_fma_f32 v199, v208, v207, v199
	v_fma_f32 v192, v208, v210, v188
	v_mov_b32_dpp v188, v188 row_half_mirror row_mask:0xf bank_mask:0xa
	ds_read_b128 v[204:207], v3 offset:39424
	v_fma_f32 v159, -v188, v200, v196
	v_fma_f32 v164, -v188, v201, v197
	v_fma_f32 v165, -v188, v202, v198
	v_fma_f32 v167, -v188, v203, v199
	v_fma_f32 v192, -v188, v209, v192
	ds_read_b128 v[188:191], v3 offset:38400
	ds_write_b32 v2, v192 offset:1472
	ds_read_b128 v[192:195], v3 offset:38656
	ds_read_b128 v[196:199], v3 offset:38912
	ds_read_b128 v[208:211], v4 offset:38400
	ds_read_b128 v[200:203], v3 offset:39168
	s_waitcnt lgkmcnt(7)
	v_mul_f32 v160, v159, v160
	v_mul_f32 v168, v159, v168
	v_fma_f32 v160, v164, v161, v160
	v_fma_f32 v168, v164, v169, v168
	v_fma_f32 v160, v165, v162, v160
	v_fma_f32 v168, v165, v170, v168
	v_fma_f32 v160, v167, v163, v160
	v_fma_f32 v168, v167, v171, v168
	v_mul_f32 v172, v159, v172
	v_add_f32_dpp v160, v160, v160 row_half_mirror row_mask:0xf bank_mask:0x5
	v_add_f32_dpp v160, v168, v168 row_half_mirror row_mask:0xf bank_mask:0xa
	v_mul_f32 v173, v164, v173
	v_mul_f32 v174, v165, v174
	v_add_f32_dpp v160, v160, v160 quad_perm:[1,0,3,2] row_mask:0xf bank_mask:0xf
	v_mul_f32 v175, v167, v175
	v_fma_f32 v172, v184, v180, v172
	v_add_f32_dpp v160, v160, v160 quad_perm:[2,3,0,1] row_mask:0xf bank_mask:0xf
	v_fma_f32 v173, v184, v181, v173
	v_fma_f32 v174, v184, v182, v174
	v_add_f32_dpp v160, v160, v160 row_ror:8 row_mask:0xf bank_mask:0xf
	v_fma_f32 v175, v184, v183, v175
	v_fma_f32 v168, v184, v186, v160
	v_mov_b32_dpp v160, v160 row_half_mirror row_mask:0xf bank_mask:0xa
	ds_read_b128 v[180:183], v3 offset:40960
	v_fma_f32 v159, -v160, v176, v172
	v_fma_f32 v164, -v160, v177, v173
	v_fma_f32 v165, -v160, v178, v174
	v_fma_f32 v167, -v160, v179, v175
	v_fma_f32 v168, -v160, v185, v168
	ds_read_b128 v[160:163], v3 offset:39936
	ds_write_b32 v2, v168 offset:1536
	ds_read_b128 v[168:171], v3 offset:40192
	ds_read_b128 v[172:175], v3 offset:40448
	ds_read_b128 v[184:187], v4 offset:39936
	ds_read_b128 v[176:179], v3 offset:40704
	s_waitcnt lgkmcnt(7)
	v_mul_f32 v188, v159, v188
	v_mul_f32 v192, v159, v192
	v_fma_f32 v188, v164, v189, v188
	v_fma_f32 v192, v164, v193, v192
	v_fma_f32 v188, v165, v190, v188
	v_fma_f32 v192, v165, v194, v192
	v_fma_f32 v188, v167, v191, v188
	v_fma_f32 v192, v167, v195, v192
	v_mul_f32 v196, v159, v196
	v_add_f32_dpp v188, v188, v188 row_half_mirror row_mask:0xf bank_mask:0x5
	v_add_f32_dpp v188, v192, v192 row_half_mirror row_mask:0xf bank_mask:0xa
	v_mul_f32 v197, v164, v197
	v_mul_f32 v198, v165, v198
	v_add_f32_dpp v188, v188, v188 quad_perm:[1,0,3,2] row_mask:0xf bank_mask:0xf
	v_mul_f32 v199, v167, v199
	v_fma_f32 v196, v208, v204, v196
	v_add_f32_dpp v188, v188, v188 quad_perm:[2,3,0,1] row_mask:0xf bank_mask:0xf
	v_fma_f32 v197, v208, v205, v197
	v_fma_f32 v198, v208, v206, v198
	v_add_f32_dpp v188, v188, v188 row_ror:8 row_mask:0xf bank_mask:0xf
	v_fma_f32 v199, v208, v207, v199
	v_fma_f32 v192, v208, v210, v188
	v_mov_b32_dpp v188, v188 row_half_mirror row_mask:0xf bank_mask:0xa
	ds_read_b128 v[204:207], v3 offset:42496
	v_fma_f32 v159, -v188, v200, v196
	v_fma_f32 v164, -v188, v201, v197
	v_fma_f32 v165, -v188, v202, v198
	v_fma_f32 v167, -v188, v203, v199
	v_fma_f32 v192, -v188, v209, v192
	ds_read_b128 v[188:191], v3 offset:41472
	ds_write_b32 v2, v192 offset:1600
	ds_read_b128 v[192:195], v3 offset:41728
	ds_read_b128 v[196:199], v3 offset:41984
	ds_read_b128 v[208:211], v4 offset:41472
	ds_read_b128 v[200:203], v3 offset:42240
	s_waitcnt lgkmcnt(7)
	v_mul_f32 v160, v159, v160
	v_mul_f32 v168, v159, v168
	v_fma_f32 v160, v164, v161, v160
	v_fma_f32 v168, v164, v169, v168
	v_fma_f32 v160, v165, v162, v160
	v_fma_f32 v168, v165, v170, v168
	v_fma_f32 v160, v167, v163, v160
	v_fma_f32 v168, v167, v171, v168
	v_mul_f32 v172, v159, v172
	v_add_f32_dpp v160, v160, v160 row_half_mirror row_mask:0xf bank_mask:0x5
	v_add_f32_dpp v160, v168, v168 row_half_mirror row_mask:0xf bank_mask:0xa
	v_mul_f32 v173, v164, v173
	v_mul_f32 v174, v165, v174
	v_add_f32_dpp v160, v160, v160 quad_perm:[1,0,3,2] row_mask:0xf bank_mask:0xf
	v_mul_f32 v175, v167, v175
	v_fma_f32 v172, v184, v180, v172
	v_add_f32_dpp v160, v160, v160 quad_perm:[2,3,0,1] row_mask:0xf bank_mask:0xf
	v_fma_f32 v173, v184, v181, v173
	v_fma_f32 v174, v184, v182, v174
	v_add_f32_dpp v160, v160, v160 row_ror:8 row_mask:0xf bank_mask:0xf
	v_fma_f32 v175, v184, v183, v175
	v_fma_f32 v168, v184, v186, v160
	v_mov_b32_dpp v160, v160 row_half_mirror row_mask:0xf bank_mask:0xa
	ds_read_b128 v[180:183], v3 offset:44032
	v_fma_f32 v159, -v160, v176, v172
	v_fma_f32 v164, -v160, v177, v173
	v_fma_f32 v165, -v160, v178, v174
	v_fma_f32 v167, -v160, v179, v175
	v_fma_f32 v168, -v160, v185, v168
	ds_read_b128 v[160:163], v3 offset:43008
	ds_write_b32 v2, v168 offset:1664
	ds_read_b128 v[168:171], v3 offset:43264
	ds_read_b128 v[172:175], v3 offset:43520
	ds_read_b128 v[184:187], v4 offset:43008
	ds_read_b128 v[176:179], v3 offset:43776
	s_waitcnt lgkmcnt(7)
; __device__ __forceinline__ float vfma(float a, float b, float c) { float d; asm("v_fma_f32 %0, %1, %2, %3" : "=v"(d) : "v"(a), "v"(b), "v"(c)); return d; }
; __device__ __forceinline__ float vnfma(float a, float b, float c) { float d; asm("v_fma_f32 %0, -%1, %2, %3" : "=v"(d) : "v"(a), "v"(b), "v"(c)); return d; }
; __device__ __forceinline__ float vmul(float a, float b) { float d; asm("v_mul_f32 %0, %1, %2" : "=v"(d) : "v"(a), "v"(b)); return d; }
; __device__ __forceinline__ float vadd(float a, float b) { float d; asm("v_add_f32 %0, %1, %2" : "=v"(d) : "v"(a), "v"(b)); return d; }
; __device__ __forceinline__ float step_compute(float (&S)[4], const StepOp& o) {
;     float d1 = vmul(S[0], o.kk[0]), d2 = vmul(S[0], o.wr[0]), e1 = vmul(S[1], o.kk[1]), e2 = vmul(S[1], o.wr[1]);
;     d1 = vfma(S[2], o.kk[2], d1); d2 = vfma(S[2], o.wr[2], d2); e1 = vfma(S[3], o.kk[3], e1); e2 = vfma(S[3], o.wr[3], e2);
;     d1 = vadd(d1, e1); d2 = vadd(d2, e2);
;     float t0, t1, t2, t3;
;     asm volatile(
;         "v_mul_f32 %[t0], %[s0], %[w0]\n\t"
;         "v_mul_f32 %[t1], %[s1], %[w1]\n\t"
;         "v_add_f32_dpp %[d1], %[d1], %[d1] quad_perm:[1,0,3,2] row_mask:0xf bank_mask:0xf bound_ctrl:1\n\t"
;         "v_add_f32_dpp %[d2], %[d2], %[d2] quad_perm:[1,0,3,2] row_mask:0xf bank_mask:0xf bound_ctrl:1\n\t"
;         "v_mul_f32 %[t2], %[s2], %[w2]\n\t"
;         "v_add_f32_dpp %[d1], %[d1], %[d1] quad_perm:[2,3,0,1] row_mask:0xf bank_mask:0xf bound_ctrl:1\n\t"
;         "v_add_f32_dpp %[d2], %[d2], %[d2] quad_perm:[2,3,0,1] row_mask:0xf bank_mask:0xf bound_ctrl:1\n\t"
;         "v_mul_f32 %[t3], %[s3], %[w3]\n\t"
;         "v_add_f32_dpp %[d1], %[d1], %[d1] row_half_mirror row_mask:0xf bank_mask:0xf bound_ctrl:1\n\t"
;         "v_add_f32_dpp %[d2], %[d2], %[d2] row_half_mirror row_mask:0xf bank_mask:0xf bound_ctrl:1\n\t"
;         "v_fma_f32 %[t0], %[v], %[k0], %[t0]\n\t"
;         "v_add_f32_dpp %[d1], %[d1], %[d1] row_mirror row_mask:0xf bank_mask:0xf bound_ctrl:1\n\t"
;         "v_add_f32_dpp %[d2], %[d2], %[d2] row_mirror row_mask:0xf bank_mask:0xf bound_ctrl:1\n\t"
;         "v_fma_f32 %[t1], %[v], %[k1], %[t1]\n\t"
;         "v_fma_f32 %[t2], %[v], %[k2], %[t2]\n\t"
;         "v_fma_f32 %[t3], %[v], %[k3], %[t3]"
;         : [t0] "=&v"(t0), [t1] "=&v"(t1), [t2] "=&v"(t2), [t3] "=&v"(t3), [d1] "+v"(d1), [d2] "+v"(d2)
	v_mul_f32 v188, v159, v188
	v_mul_f32 v192, v159, v192
	v_fma_f32 v188, v164, v189, v188
	v_fma_f32 v192, v164, v193, v192
	v_fma_f32 v188, v165, v190, v188
	v_fma_f32 v192, v165, v194, v192
	v_fma_f32 v188, v167, v191, v188
	v_fma_f32 v192, v167, v195, v192
	v_mul_f32 v196, v159, v196
	v_add_f32_dpp v188, v188, v188 row_half_mirror row_mask:0xf bank_mask:0x5
	v_add_f32_dpp v188, v192, v192 row_half_mirror row_mask:0xf bank_mask:0xa
	v_mul_f32 v197, v164, v197
	v_mul_f32 v198, v165, v198
	v_add_f32_dpp v188, v188, v188 quad_perm:[1,0,3,2] row_mask:0xf bank_mask:0xf
	v_mul_f32 v199, v167, v199
	v_fma_f32 v196, v208, v204, v196
	v_add_f32_dpp v188, v188, v188 quad_perm:[2,3,0,1] row_mask:0xf bank_mask:0xf
	v_fma_f32 v197, v208, v205, v197
	v_fma_f32 v198, v208, v206, v198
	v_add_f32_dpp v188, v188, v188 row_ror:8 row_mask:0xf bank_mask:0xf
	v_fma_f32 v199, v208, v207, v199
	v_fma_f32 v192, v208, v210, v188
	v_mov_b32_dpp v188, v188 row_half_mirror row_mask:0xf bank_mask:0xa
	ds_read_b128 v[204:207], v3 offset:45568
	v_fma_f32 v159, -v188, v200, v196
	v_fma_f32 v164, -v188, v201, v197
	v_fma_f32 v165, -v188, v202, v198
	v_fma_f32 v167, -v188, v203, v199
	v_fma_f32 v192, -v188, v209, v192
	ds_read_b128 v[188:191], v3 offset:44544
	ds_write_b32 v2, v192 offset:1728
	ds_read_b128 v[192:195], v3 offset:44800
	ds_read_b128 v[196:199], v3 offset:45056
	ds_read_b128 v[208:211], v4 offset:44544
	ds_read_b128 v[200:203], v3 offset:45312
	s_waitcnt lgkmcnt(7)
	v_mul_f32 v160, v159, v160
	v_mul_f32 v168, v159, v168
	v_fma_f32 v160, v164, v161, v160
	v_fma_f32 v168, v164, v169, v168
	v_fma_f32 v160, v165, v162, v160
	v_fma_f32 v168, v165, v170, v168
	v_fma_f32 v160, v167, v163, v160
	v_fma_f32 v168, v167, v171, v168
	v_mul_f32 v172, v159, v172
	v_add_f32_dpp v160, v160, v160 row_half_mirror row_mask:0xf bank_mask:0x5
	v_add_f32_dpp v160, v168, v168 row_half_mirror row_mask:0xf bank_mask:0xa
	v_mul_f32 v173, v164, v173
	v_mul_f32 v174, v165, v174
	v_add_f32_dpp v160, v160, v160 quad_perm:[1,0,3,2] row_mask:0xf bank_mask:0xf
	v_mul_f32 v175, v167, v175
	v_fma_f32 v172, v184, v180, v172
	v_add_f32_dpp v160, v160, v160 quad_perm:[2,3,0,1] row_mask:0xf bank_mask:0xf
	v_fma_f32 v173, v184, v181, v173
	v_fma_f32 v174, v184, v182, v174
	v_add_f32_dpp v160, v160, v160 row_ror:8 row_mask:0xf bank_mask:0xf
	v_fma_f32 v175, v184, v183, v175
	v_fma_f32 v168, v184, v186, v160
	v_mov_b32_dpp v160, v160 row_half_mirror row_mask:0xf bank_mask:0xa
	ds_read_b128 v[180:183], v3 offset:47104
	v_fma_f32 v159, -v160, v176, v172
	v_fma_f32 v164, -v160, v177, v173
	v_fma_f32 v165, -v160, v178, v174
	v_fma_f32 v167, -v160, v179, v175
	v_fma_f32 v168, -v160, v185, v168
	ds_read_b128 v[160:163], v3 offset:46080
	ds_write_b32 v2, v168 offset:1792
	ds_read_b128 v[168:171], v3 offset:46336
	ds_read_b128 v[172:175], v3 offset:46592
	ds_read_b128 v[184:187], v4 offset:46080
	ds_read_b128 v[176:179], v3 offset:46848
	s_waitcnt lgkmcnt(7)
	v_mul_f32 v188, v159, v188
	v_mul_f32 v192, v159, v192
	v_fma_f32 v188, v164, v189, v188
	v_fma_f32 v192, v164, v193, v192
	v_fma_f32 v188, v165, v190, v188
	v_fma_f32 v192, v165, v194, v192
	v_fma_f32 v188, v167, v191, v188
	v_fma_f32 v192, v167, v195, v192
	v_mul_f32 v196, v159, v196
	v_add_f32_dpp v188, v188, v188 row_half_mirror row_mask:0xf bank_mask:0x5
	v_add_f32_dpp v188, v192, v192 row_half_mirror row_mask:0xf bank_mask:0xa
	v_mul_f32 v197, v164, v197
	v_mul_f32 v198, v165, v198
	v_add_f32_dpp v188, v188, v188 quad_perm:[1,0,3,2] row_mask:0xf bank_mask:0xf
	v_mul_f32 v199, v167, v199
	v_fma_f32 v196, v208, v204, v196
	v_add_f32_dpp v188, v188, v188 quad_perm:[2,3,0,1] row_mask:0xf bank_mask:0xf
	v_fma_f32 v197, v208, v205, v197
	v_fma_f32 v198, v208, v206, v198
	v_add_f32_dpp v188, v188, v188 row_ror:8 row_mask:0xf bank_mask:0xf
	v_fma_f32 v199, v208, v207, v199
	v_fma_f32 v192, v208, v210, v188
	v_mov_b32_dpp v188, v188 row_half_mirror row_mask:0xf bank_mask:0xa
	ds_read_b128 v[204:207], v3 offset:48640
	v_fma_f32 v159, -v188, v200, v196
	v_fma_f32 v164, -v188, v201, v197
	v_fma_f32 v165, -v188, v202, v198
	v_fma_f32 v167, -v188, v203, v199
	v_fma_f32 v192, -v188, v209, v192
	ds_read_b128 v[188:191], v3 offset:47616
	ds_write_b32 v2, v192 offset:1856
	ds_read_b128 v[192:195], v3 offset:47872
	ds_read_b128 v[196:199], v3 offset:48128
	ds_read_b128 v[208:211], v4 offset:47616
	ds_read_b128 v[200:203], v3 offset:48384
	s_waitcnt lgkmcnt(7)
	v_mul_f32 v160, v159, v160
	v_mul_f32 v168, v159, v168
	v_fma_f32 v160, v164, v161, v160
	v_fma_f32 v168, v164, v169, v168
	v_fma_f32 v160, v165, v162, v160
	v_fma_f32 v168, v165, v170, v168
	v_fma_f32 v160, v167, v163, v160
	v_fma_f32 v168, v167, v171, v168
	v_mul_f32 v172, v159, v172
	v_add_f32_dpp v160, v160, v160 row_half_mirror row_mask:0xf bank_mask:0x5
	v_add_f32_dpp v160, v168, v168 row_half_mirror row_mask:0xf bank_mask:0xa
	v_mul_f32 v173, v164, v173
	v_mul_f32 v174, v165, v174
	v_add_f32_dpp v160, v160, v160 quad_perm:[1,0,3,2] row_mask:0xf bank_mask:0xf
	v_mul_f32 v175, v167, v175
	v_fma_f32 v172, v184, v180, v172
	v_add_f32_dpp v160, v160, v160 quad_perm:[2,3,0,1] row_mask:0xf bank_mask:0xf
	v_fma_f32 v173, v184, v181, v173
	v_fma_f32 v174, v184, v182, v174
	v_add_f32_dpp v160, v160, v160 row_ror:8 row_mask:0xf bank_mask:0xf
	v_fma_f32 v175, v184, v183, v175
	v_fma_f32 v168, v184, v186, v160
	v_mov_b32_dpp v160, v160 row_half_mirror row_mask:0xf bank_mask:0xa
	v_fma_f32 v159, -v160, v176, v172
	v_fma_f32 v164, -v160, v177, v173
	v_fma_f32 v165, -v160, v178, v174
	v_fma_f32 v167, -v160, v179, v175
	v_fma_f32 v168, -v160, v185, v168
	ds_write_b32 v2, v168 offset:1920
	s_waitcnt lgkmcnt(1)
	v_mul_f32 v188, v159, v188
	v_mul_f32 v192, v159, v192
	v_fma_f32 v188, v164, v189, v188
	v_fma_f32 v192, v164, v193, v192
	v_fma_f32 v188, v165, v190, v188
	v_fma_f32 v192, v165, v194, v192
	v_fma_f32 v188, v167, v191, v188
	v_fma_f32 v192, v167, v195, v192
	v_mul_f32 v196, v159, v196
	v_add_f32_dpp v188, v188, v188 row_half_mirror row_mask:0xf bank_mask:0x5
	v_add_f32_dpp v188, v192, v192 row_half_mirror row_mask:0xf bank_mask:0xa
	v_mul_f32 v197, v164, v197
	v_mul_f32 v198, v165, v198
	v_add_f32_dpp v188, v188, v188 quad_perm:[1,0,3,2] row_mask:0xf bank_mask:0xf
	v_mul_f32 v199, v167, v199
	v_fma_f32 v196, v208, v204, v196
	v_add_f32_dpp v188, v188, v188 quad_perm:[2,3,0,1] row_mask:0xf bank_mask:0xf
	v_fma_f32 v197, v208, v205, v197
	v_fma_f32 v198, v208, v206, v198
	v_add_f32_dpp v188, v188, v188 row_ror:8 row_mask:0xf bank_mask:0xf
	v_fma_f32 v199, v208, v207, v199
	v_fma_f32 v192, v208, v210, v188
	v_mov_b32_dpp v188, v188 row_half_mirror row_mask:0xf bank_mask:0xa
	v_fma_f32 v3, -v188, v200, v196
	v_fma_f32 v4, -v188, v201, v197
	v_fma_f32 v115, -v188, v202, v198
	v_fma_f32 v129, -v188, v203, v199
	v_fma_f32 v192, -v188, v209, v192
	ds_write_b32 v2, v192 offset:1984

; __device__ __forceinline__ float vfma(float a, float b, float c) { float d; asm("v_fma_f32 %0, %1, %2, %3" : "=v"(d) : "v"(a), "v"(b), "v"(c)); return d; }
; __device__ __forceinline__ float vnfma(float a, float b, float c) { float d; asm("v_fma_f32 %0, -%1, %2, %3" : "=v"(d) : "v"(a), "v"(b), "v"(c)); return d; }
; __device__ __forceinline__ float vmul(float a, float b) { float d; asm("v_mul_f32 %0, %1, %2" : "=v"(d) : "v"(a), "v"(b)); return d; }
; __device__ __forceinline__ float vadd(float a, float b) { float d; asm("v_add_f32 %0, %1, %2" : "=v"(d) : "v"(a), "v"(b)); return d; }
; __device__ __forceinline__ float step_compute(float (&S)[4], const StepOp& o) {
;     float d1 = vmul(S[0], o.kk[0]), d2 = vmul(S[0], o.wr[0]), e1 = vmul(S[1], o.kk[1]), e2 = vmul(S[1], o.wr[1]);
;     d1 = vfma(S[2], o.kk[2], d1); d2 = vfma(S[2], o.wr[2], d2); e1 = vfma(S[3], o.kk[3], e1); e2 = vfma(S[3], o.wr[3], e2);
;     d1 = vadd(d1, e1); d2 = vadd(d2, e2);
;     float t0, t1, t2, t3;
;     asm volatile(
;         "v_mul_f32 %[t0], %[s0], %[w0]\n\t"
;         "v_mul_f32 %[t1], %[s1], %[w1]\n\t"
;         "v_add_f32_dpp %[d1], %[d1], %[d1] quad_perm:[1,0,3,2] row_mask:0xf bank_mask:0xf bound_ctrl:1\n\t"
;         "v_add_f32_dpp %[d2], %[d2], %[d2] quad_perm:[1,0,3,2] row_mask:0xf bank_mask:0xf bound_ctrl:1\n\t"
;         "v_mul_f32 %[t2], %[s2], %[w2]\n\t"
;         "v_add_f32_dpp %[d1], %[d1], %[d1] quad_perm:[2,3,0,1] row_mask:0xf bank_mask:0xf bound_ctrl:1\n\t"
;         "v_add_f32_dpp %[d2], %[d2], %[d2] quad_perm:[2,3,0,1] row_mask:0xf bank_mask:0xf bound_ctrl:1\n\t"
;         "v_mul_f32 %[t3], %[s3], %[w3]\n\t"
;         "v_add_f32_dpp %[d1], %[d1], %[d1] row_half_mirror row_mask:0xf bank_mask:0xf bound_ctrl:1\n\t"
; __device__ __forceinline__ void scan_quarter(LAS unsigned char* lds, const ScanConst& C, int m0, int T, int h, int quarter, const float* shift_prev  , const float* S0p  , float* Sout, const float* cWg, const float* cWu, const float* cWd, bf16* cWGU, bf16* cWD, int& conv_next, int conv_stride, int wa ...
;     ...
;         LAS float* cur = (c & 1) ? buf1 : buf0; LAS float* nxt = (c & 1) ? buf0 : buf1;
;         if (scanner) {
;             LAS float* yb = ybuf + (c & 1) * TC * 16 + srow;
;             const LAS float* sp = cur + part * 4; const LAS float* qp = cur + 320 + srow * 4;
;             StepOp A, B;
;             step_load(A, sp, qp);
.LBB0_818:
	s_and_b32 s43, s18, 1
	s_cmp_eq_u32 s43, 0
	s_cselect_b64 s[30:31], -1, 0
	s_and_b64 vcc, exec, s[6:7]
	s_mov_b64 s[76:77], -1
	s_cbranch_vccnz .LBB0_820
	s_and_b64 s[76:77], s[30:31], exec
	s_cselect_b32 s76, 0, s91
	v_lshl_add_u32 v2, s43, 11, v148
	v_add_u32_e32 v3, s76, v149
	s_cselect_b32 s43, s93, s92
	v_add_u32_e32 v4, s43, v150
	ds_read_b128 v[160:163], v3
	ds_read_b128 v[168:171], v3 offset:256
	ds_read_b128 v[172:175], v3 offset:512
	ds_read_b128 v[180:183], v3 offset:1024
	ds_read_b128 v[184:187], v4
	ds_read_b128 v[176:179], v3 offset:768
	s_mov_b64 s[76:77], 0
	v_mbcnt_lo_u32_b32 v115, -1, 0
	v_mbcnt_hi_u32_b32 v115, -1, v115
	v_and_b32_e32 v115, 4, v115
	v_xor_b32_e32 v115, 4, v115
	v_mul_u32_u24_e32 v115, 0x2700, v115
	v_add_u32_e32 v2, v2, v115
	ds_read_b128 v[188:191], v3 offset:1536
	ds_read_b128 v[192:195], v3 offset:1792
	ds_read_b128 v[196:199], v3 offset:2048
	ds_read_b128 v[204:207], v3 offset:2560
	ds_read_b128 v[208:211], v4 offset:1536
	ds_read_b128 v[200:203], v3 offset:2304
	s_waitcnt lgkmcnt(6)
	v_mul_f32 v160, v78, v160
	v_mul_f32 v168, v78, v168
	v_fma_f32 v160, v79, v161, v160
	v_fma_f32 v168, v79, v169, v168
	v_fma_f32 v160, v80, v162, v160
	v_fma_f32 v168, v80, v170, v168
	v_fma_f32 v160, v81, v163, v160
	v_fma_f32 v168, v81, v171, v168
	v_mul_f32 v172, v78, v172
	v_add_f32_dpp v160, v160, v160 row_half_mirror row_mask:0xf bank_mask:0x5
	v_add_f32_dpp v160, v168, v168 row_half_mirror row_mask:0xf bank_mask:0xa
	v_mul_f32 v173, v79, v173
	v_mul_f32 v174, v80, v174
	v_add_f32_dpp v160, v160, v160 quad_perm:[1,0,3,2] row_mask:0xf bank_mask:0xf
	v_mul_f32 v175, v81, v175
	v_fma_f32 v172, v184, v180, v172
	v_add_f32_dpp v160, v160, v160 quad_perm:[2,3,0,1] row_mask:0xf bank_mask:0xf
	v_fma_f32 v173, v184, v181, v173
	v_fma_f32 v174, v184, v182, v174
	v_add_f32_dpp v160, v160, v160 row_ror:8 row_mask:0xf bank_mask:0xf
	v_fma_f32 v175, v184, v183, v175
	v_fma_f32 v168, v184, v186, v160
	v_mov_b32_dpp v160, v160 row_half_mirror row_mask:0xf bank_mask:0xa
	ds_read_b128 v[180:183], v3 offset:4096
	v_fma_f32 v159, -v160, v176, v172
	v_fma_f32 v164, -v160, v177, v173
	v_fma_f32 v165, -v160, v178, v174
	v_fma_f32 v167, -v160, v179, v175
	v_fma_f32 v168, -v160, v185, v168
	ds_read_b128 v[160:163], v3 offset:3072
	ds_write_b32 v2, v168
	ds_read_b128 v[168:171], v3 offset:3328
	ds_read_b128 v[172:175], v3 offset:3584
	ds_read_b128 v[184:187], v4 offset:3072
	ds_read_b128 v[176:179], v3 offset:3840
	s_waitcnt lgkmcnt(7)
	v_mul_f32 v188, v159, v188
	v_mul_f32 v192, v159, v192
	v_fma_f32 v188, v164, v189, v188
	v_fma_f32 v192, v164, v193, v192
	v_fma_f32 v188, v165, v190, v188
	v_fma_f32 v192, v165, v194, v192
	v_fma_f32 v188, v167, v191, v188
	v_fma_f32 v192, v167, v195, v192
	v_mul_f32 v196, v159, v196
	v_add_f32_dpp v188, v188, v188 row_half_mirror row_mask:0xf bank_mask:0x5
	v_add_f32_dpp v188, v192, v192 row_half_mirror row_mask:0xf bank_mask:0xa
	v_mul_f32 v197, v164, v197
	v_mul_f32 v198, v165, v198
	v_add_f32_dpp v188, v188, v188 quad_perm:[1,0,3,2] row_mask:0xf bank_mask:0xf
	v_mul_f32 v199, v167, v199
	v_fma_f32 v196, v208, v204, v196
	v_add_f32_dpp v188, v188, v188 quad_perm:[2,3,0,1] row_mask:0xf bank_mask:0xf
	v_fma_f32 v197, v208, v205, v197
	v_fma_f32 v198, v208, v206, v198
	v_add_f32_dpp v188, v188, v188 row_ror:8 row_mask:0xf bank_mask:0xf
	v_fma_f32 v199, v208, v207, v199
	v_fma_f32 v192, v208, v210, v188
	v_mov_b32_dpp v188, v188 row_half_mirror row_mask:0xf bank_mask:0xa
	ds_read_b128 v[204:207], v3 offset:5632
	v_fma_f32 v159, -v188, v200, v196
	v_fma_f32 v164, -v188, v201, v197
	v_fma_f32 v165, -v188, v202, v198
	v_fma_f32 v167, -v188, v203, v199
	v_fma_f32 v192, -v188, v209, v192
	ds_read_b128 v[188:191], v3 offset:4608
	ds_write_b32 v2, v192 offset:64
	ds_read_b128 v[192:195], v3 offset:4864
	ds_read_b128 v[196:199], v3 offset:5120
	ds_read_b128 v[208:211], v4 offset:4608
	ds_read_b128 v[200:203], v3 offset:5376
	s_waitcnt lgkmcnt(7)
	v_mul_f32 v160, v159, v160
	v_mul_f32 v168, v159, v168
	v_fma_f32 v160, v164, v161, v160
	v_fma_f32 v168, v164, v169, v168
	v_fma_f32 v160, v165, v162, v160
	v_fma_f32 v168, v165, v170, v168
	v_fma_f32 v160, v167, v163, v160
	v_fma_f32 v168, v167, v171, v168
	v_mul_f32 v172, v159, v172
	v_add_f32_dpp v160, v160, v160 row_half_mirror row_mask:0xf bank_mask:0x5
	v_add_f32_dpp v160, v168, v168 row_half_mirror row_mask:0xf bank_mask:0xa
	v_mul_f32 v173, v164, v173
	v_mul_f32 v174, v165, v174
	v_add_f32_dpp v160, v160, v160 quad_perm:[1,0,3,2] row_mask:0xf bank_mask:0xf
	v_mul_f32 v175, v167, v175
	v_fma_f32 v172, v184, v180, v172
	v_add_f32_dpp v160, v160, v160 quad_perm:[2,3,0,1] row_mask:0xf bank_mask:0xf
	v_fma_f32 v173, v184, v181, v173
	v_fma_f32 v174, v184, v182, v174
	v_add_f32_dpp v160, v160, v160 row_ror:8 row_mask:0xf bank_mask:0xf
	v_fma_f32 v175, v184, v183, v175
	v_fma_f32 v168, v184, v186, v160
	v_mov_b32_dpp v160, v160 row_half_mirror row_mask:0xf bank_mask:0xa
	ds_read_b128 v[180:183], v3 offset:7168
	v_fma_f32 v159, -v160, v176, v172
	v_fma_f32 v164, -v160, v177, v173
	v_fma_f32 v165, -v160, v178, v174
	v_fma_f32 v167, -v160, v179, v175
	v_fma_f32 v168, -v160, v185, v168
	ds_read_b128 v[160:163], v3 offset:6144
	ds_write_b32 v2, v168 offset:128
	ds_read_b128 v[168:171], v3 offset:6400
	ds_read_b128 v[172:175], v3 offset:6656
	ds_read_b128 v[184:187], v4 offset:6144
	ds_read_b128 v[176:179], v3 offset:6912
	s_waitcnt lgkmcnt(7)
; __device__ __forceinline__ float vfma(float a, float b, float c) { float d; asm("v_fma_f32 %0, %1, %2, %3" : "=v"(d) : "v"(a), "v"(b), "v"(c)); return d; }
; __device__ __forceinline__ float vnfma(float a, float b, float c) { float d; asm("v_fma_f32 %0, -%1, %2, %3" : "=v"(d) : "v"(a), "v"(b), "v"(c)); return d; }
; __device__ __forceinline__ float vmul(float a, float b) { float d; asm("v_mul_f32 %0, %1, %2" : "=v"(d) : "v"(a), "v"(b)); return d; }
; __device__ __forceinline__ float vadd(float a, float b) { float d; asm("v_add_f32 %0, %1, %2" : "=v"(d) : "v"(a), "v"(b)); return d; }
; __device__ __forceinline__ float step_compute(float (&S)[4], const StepOp& o) {
;     float d1 = vmul(S[0], o.kk[0]), d2 = vmul(S[0], o.wr[0]), e1 = vmul(S[1], o.kk[1]), e2 = vmul(S[1], o.wr[1]);
;     d1 = vfma(S[2], o.kk[2], d1); d2 = vfma(S[2], o.wr[2], d2); e1 = vfma(S[3], o.kk[3], e1); e2 = vfma(S[3], o.wr[3], e2);
;     d1 = vadd(d1, e1); d2 = vadd(d2, e2);
;     float t0, t1, t2, t3;
;     asm volatile(
;         "v_mul_f32 %[t0], %[s0], %[w0]\n\t"
;         "v_mul_f32 %[t1], %[s1], %[w1]\n\t"
;         "v_add_f32_dpp %[d1], %[d1], %[d1] quad_perm:[1,0,3,2] row_mask:0xf bank_mask:0xf bound_ctrl:1\n\t"
;         "v_add_f32_dpp %[d2], %[d2], %[d2] quad_perm:[1,0,3,2] row_mask:0xf bank_mask:0xf bound_ctrl:1\n\t"
;         "v_mul_f32 %[t2], %[s2], %[w2]\n\t"
;         "v_add_f32_dpp %[d1], %[d1], %[d1] quad_perm:[2,3,0,1] row_mask:0xf bank_mask:0xf bound_ctrl:1\n\t"
;         "v_add_f32_dpp %[d2], %[d2], %[d2] quad_perm:[2,3,0,1] row_mask:0xf bank_mask:0xf bound_ctrl:1\n\t"
;         "v_mul_f32 %[t3], %[s3], %[w3]\n\t"
;         "v_add_f32_dpp %[d1], %[d1], %[d1] row_half_mirror row_mask:0xf bank_mask:0xf bound_ctrl:1\n\t"
;         "v_add_f32_dpp %[d2], %[d2], %[d2] row_half_mirror row_mask:0xf bank_mask:0xf bound_ctrl:1\n\t"
;         "v_fma_f32 %[t0], %[v], %[k0], %[t0]\n\t"
;         "v_add_f32_dpp %[d1], %[d1], %[d1] row_mirror row_mask:0xf bank_mask:0xf bound_ctrl:1\n\t"
;         "v_add_f32_dpp %[d2], %[d2], %[d2] row_mirror row_mask:0xf bank_mask:0xf bound_ctrl:1\n\t"
;         "v_fma_f32 %[t1], %[v], %[k1], %[t1]\n\t"
;         "v_fma_f32 %[t2], %[v], %[k2], %[t2]\n\t"
;         "v_fma_f32 %[t3], %[v], %[k3], %[t3]"
;         : [t0] "=&v"(t0), [t1] "=&v"(t1), [t2] "=&v"(t2), [t3] "=&v"(t3), [d1] "+v"(d1), [d2] "+v"(d2)
	v_mul_f32 v188, v159, v188
	v_mul_f32 v192, v159, v192
	v_fma_f32 v188, v164, v189, v188
	v_fma_f32 v192, v164, v193, v192
	v_fma_f32 v188, v165, v190, v188
	v_fma_f32 v192, v165, v194, v192
	v_fma_f32 v188, v167, v191, v188
	v_fma_f32 v192, v167, v195, v192
	v_mul_f32 v196, v159, v196
	v_add_f32_dpp v188, v188, v188 row_half_mirror row_mask:0xf bank_mask:0x5
	v_add_f32_dpp v188, v192, v192 row_half_mirror row_mask:0xf bank_mask:0xa
	v_mul_f32 v197, v164, v197
	v_mul_f32 v198, v165, v198
	v_add_f32_dpp v188, v188, v188 quad_perm:[1,0,3,2] row_mask:0xf bank_mask:0xf
	v_mul_f32 v199, v167, v199
	v_fma_f32 v196, v208, v204, v196
	v_add_f32_dpp v188, v188, v188 quad_perm:[2,3,0,1] row_mask:0xf bank_mask:0xf
	v_fma_f32 v197, v208, v205, v197
	v_fma_f32 v198, v208, v206, v198
	v_add_f32_dpp v188, v188, v188 row_ror:8 row_mask:0xf bank_mask:0xf
	v_fma_f32 v199, v208, v207, v199
	v_fma_f32 v192, v208, v210, v188
	v_mov_b32_dpp v188, v188 row_half_mirror row_mask:0xf bank_mask:0xa
	ds_read_b128 v[204:207], v3 offset:8704
	v_fma_f32 v159, -v188, v200, v196
	v_fma_f32 v164, -v188, v201, v197
	v_fma_f32 v165, -v188, v202, v198
	v_fma_f32 v167, -v188, v203, v199
	v_fma_f32 v192, -v188, v209, v192
	ds_read_b128 v[188:191], v3 offset:7680
	ds_write_b32 v2, v192 offset:192
	ds_read_b128 v[192:195], v3 offset:7936
	ds_read_b128 v[196:199], v3 offset:8192
	ds_read_b128 v[208:211], v4 offset:7680
	ds_read_b128 v[200:203], v3 offset:8448
	s_waitcnt lgkmcnt(7)
	v_mul_f32 v160, v159, v160
	v_mul_f32 v168, v159, v168
	v_fma_f32 v160, v164, v161, v160
	v_fma_f32 v168, v164, v169, v168
	v_fma_f32 v160, v165, v162, v160
	v_fma_f32 v168, v165, v170, v168
	v_fma_f32 v160, v167, v163, v160
	v_fma_f32 v168, v167, v171, v168
	v_mul_f32 v172, v159, v172
	v_add_f32_dpp v160, v160, v160 row_half_mirror row_mask:0xf bank_mask:0x5
	v_add_f32_dpp v160, v168, v168 row_half_mirror row_mask:0xf bank_mask:0xa
	v_mul_f32 v173, v164, v173
	v_mul_f32 v174, v165, v174
	v_add_f32_dpp v160, v160, v160 quad_perm:[1,0,3,2] row_mask:0xf bank_mask:0xf
	v_mul_f32 v175, v167, v175
	v_fma_f32 v172, v184, v180, v172
	v_add_f32_dpp v160, v160, v160 quad_perm:[2,3,0,1] row_mask:0xf bank_mask:0xf
	v_fma_f32 v173, v184, v181, v173
	v_fma_f32 v174, v184, v182, v174
	v_add_f32_dpp v160, v160, v160 row_ror:8 row_mask:0xf bank_mask:0xf
	v_fma_f32 v175, v184, v183, v175
	v_fma_f32 v168, v184, v186, v160
	v_mov_b32_dpp v160, v160 row_half_mirror row_mask:0xf bank_mask:0xa
	ds_read_b128 v[180:183], v3 offset:10240
	v_fma_f32 v159, -v160, v176, v172
	v_fma_f32 v164, -v160, v177, v173
	v_fma_f32 v165, -v160, v178, v174
	v_fma_f32 v167, -v160, v179, v175
	v_fma_f32 v168, -v160, v185, v168
	ds_read_b128 v[160:163], v3 offset:9216
	ds_write_b32 v2, v168 offset:256
	ds_read_b128 v[168:171], v3 offset:9472
	ds_read_b128 v[172:175], v3 offset:9728
	ds_read_b128 v[184:187], v4 offset:9216
	ds_read_b128 v[176:179], v3 offset:9984
	s_waitcnt lgkmcnt(7)
	v_mul_f32 v188, v159, v188
	v_mul_f32 v192, v159, v192
	v_fma_f32 v188, v164, v189, v188
	v_fma_f32 v192, v164, v193, v192
	v_fma_f32 v188, v165, v190, v188
	v_fma_f32 v192, v165, v194, v192
	v_fma_f32 v188, v167, v191, v188
	v_fma_f32 v192, v167, v195, v192
	v_mul_f32 v196, v159, v196
	v_add_f32_dpp v188, v188, v188 row_half_mirror row_mask:0xf bank_mask:0x5
	v_add_f32_dpp v188, v192, v192 row_half_mirror row_mask:0xf bank_mask:0xa
	v_mul_f32 v197, v164, v197
	v_mul_f32 v198, v165, v198
	v_add_f32_dpp v188, v188, v188 quad_perm:[1,0,3,2] row_mask:0xf bank_mask:0xf
	v_mul_f32 v199, v167, v199
	v_fma_f32 v196, v208, v204, v196
	v_add_f32_dpp v188, v188, v188 quad_perm:[2,3,0,1] row_mask:0xf bank_mask:0xf
	v_fma_f32 v197, v208, v205, v197
	v_fma_f32 v198, v208, v206, v198
	v_add_f32_dpp v188, v188, v188 row_ror:8 row_mask:0xf bank_mask:0xf
	v_fma_f32 v199, v208, v207, v199
	v_fma_f32 v192, v208, v210, v188
	v_mov_b32_dpp v188, v188 row_half_mirror row_mask:0xf bank_mask:0xa
	ds_read_b128 v[204:207], v3 offset:11776
	v_fma_f32 v159, -v188, v200, v196
	v_fma_f32 v164, -v188, v201, v197
	v_fma_f32 v165, -v188, v202, v198
	v_fma_f32 v167, -v188, v203, v199
	v_fma_f32 v192, -v188, v209, v192
	ds_read_b128 v[188:191], v3 offset:10752
	ds_write_b32 v2, v192 offset:320
	ds_read_b128 v[192:195], v3 offset:11008
	ds_read_b128 v[196:199], v3 offset:11264
	ds_read_b128 v[208:211], v4 offset:10752
	ds_read_b128 v[200:203], v3 offset:11520
	s_waitcnt lgkmcnt(7)
	v_mul_f32 v160, v159, v160
	v_mul_f32 v168, v159, v168
	v_fma_f32 v160, v164, v161, v160
	v_fma_f32 v168, v164, v169, v168
	v_fma_f32 v160, v165, v162, v160
	v_fma_f32 v168, v165, v170, v168
	v_fma_f32 v160, v167, v163, v160
	v_fma_f32 v168, v167, v171, v168
	v_mul_f32 v172, v159, v172
	v_add_f32_dpp v160, v160, v160 row_half_mirror row_mask:0xf bank_mask:0x5
	v_add_f32_dpp v160, v168, v168 row_half_mirror row_mask:0xf bank_mask:0xa
	v_mul_f32 v173, v164, v173
	v_mul_f32 v174, v165, v174
	v_add_f32_dpp v160, v160, v160 quad_perm:[1,0,3,2] row_mask:0xf bank_mask:0xf
	v_mul_f32 v175, v167, v175
	v_fma_f32 v172, v184, v180, v172
	v_add_f32_dpp v160, v160, v160 quad_perm:[2,3,0,1] row_mask:0xf bank_mask:0xf
	v_fma_f32 v173, v184, v181, v173
	v_fma_f32 v174, v184, v182, v174
	v_add_f32_dpp v160, v160, v160 row_ror:8 row_mask:0xf bank_mask:0xf
	v_fma_f32 v175, v184, v183, v175
	v_fma_f32 v168, v184, v186, v160
	v_mov_b32_dpp v160, v160 row_half_mirror row_mask:0xf bank_mask:0xa
	ds_read_b128 v[180:183], v3 offset:13312
	v_fma_f32 v159, -v160, v176, v172
	v_fma_f32 v164, -v160, v177, v173
	v_fma_f32 v165, -v160, v178, v174
	v_fma_f32 v167, -v160, v179, v175
	v_fma_f32 v168, -v160, v185, v168
	ds_read_b128 v[160:163], v3 offset:12288
	ds_write_b32 v2, v168 offset:384
	ds_read_b128 v[168:171], v3 offset:12544
	ds_read_b128 v[172:175], v3 offset:12800
	ds_read_b128 v[184:187], v4 offset:12288
	ds_read_b128 v[176:179], v3 offset:13056
	s_waitcnt lgkmcnt(7)
; __device__ __forceinline__ float vfma(float a, float b, float c) { float d; asm("v_fma_f32 %0, %1, %2, %3" : "=v"(d) : "v"(a), "v"(b), "v"(c)); return d; }
; __device__ __forceinline__ float vnfma(float a, float b, float c) { float d; asm("v_fma_f32 %0, -%1, %2, %3" : "=v"(d) : "v"(a), "v"(b), "v"(c)); return d; }
; __device__ __forceinline__ float vmul(float a, float b) { float d; asm("v_mul_f32 %0, %1, %2" : "=v"(d) : "v"(a), "v"(b)); return d; }
; __device__ __forceinline__ float vadd(float a, float b) { float d; asm("v_add_f32 %0, %1, %2" : "=v"(d) : "v"(a), "v"(b)); return d; }
; __device__ __forceinline__ float step_compute(float (&S)[4], const StepOp& o) {
;     float d1 = vmul(S[0], o.kk[0]), d2 = vmul(S[0], o.wr[0]), e1 = vmul(S[1], o.kk[1]), e2 = vmul(S[1], o.wr[1]);
;     d1 = vfma(S[2], o.kk[2], d1); d2 = vfma(S[2], o.wr[2], d2); e1 = vfma(S[3], o.kk[3], e1); e2 = vfma(S[3], o.wr[3], e2);
;     d1 = vadd(d1, e1); d2 = vadd(d2, e2);
;     float t0, t1, t2, t3;
;     asm volatile(
;         "v_mul_f32 %[t0], %[s0], %[w0]\n\t"
;         "v_mul_f32 %[t1], %[s1], %[w1]\n\t"
;         "v_add_f32_dpp %[d1], %[d1], %[d1] quad_perm:[1,0,3,2] row_mask:0xf bank_mask:0xf bound_ctrl:1\n\t"
;         "v_add_f32_dpp %[d2], %[d2], %[d2] quad_perm:[1,0,3,2] row_mask:0xf bank_mask:0xf bound_ctrl:1\n\t"
;         "v_mul_f32 %[t2], %[s2], %[w2]\n\t"
;         "v_add_f32_dpp %[d1], %[d1], %[d1] quad_perm:[2,3,0,1] row_mask:0xf bank_mask:0xf bound_ctrl:1\n\t"
;         "v_add_f32_dpp %[d2], %[d2], %[d2] quad_perm:[2,3,0,1] row_mask:0xf bank_mask:0xf bound_ctrl:1\n\t"
;         "v_mul_f32 %[t3], %[s3], %[w3]\n\t"
;         "v_add_f32_dpp %[d1], %[d1], %[d1] row_half_mirror row_mask:0xf bank_mask:0xf bound_ctrl:1\n\t"
;         "v_add_f32_dpp %[d2], %[d2], %[d2] row_half_mirror row_mask:0xf bank_mask:0xf bound_ctrl:1\n\t"
;         "v_fma_f32 %[t0], %[v], %[k0], %[t0]\n\t"
;         "v_add_f32_dpp %[d1], %[d1], %[d1] row_mirror row_mask:0xf bank_mask:0xf bound_ctrl:1\n\t"
;         "v_add_f32_dpp %[d2], %[d2], %[d2] row_mirror row_mask:0xf bank_mask:0xf bound_ctrl:1\n\t"
;         "v_fma_f32 %[t1], %[v], %[k1], %[t1]\n\t"
;         "v_fma_f32 %[t2], %[v], %[k2], %[t2]\n\t"
;         "v_fma_f32 %[t3], %[v], %[k3], %[t3]"
;         : [t0] "=&v"(t0), [t1] "=&v"(t1), [t2] "=&v"(t2), [t3] "=&v"(t3), [d1] "+v"(d1), [d2] "+v"(d2)
	v_mul_f32 v188, v159, v188
	v_mul_f32 v192, v159, v192
	v_fma_f32 v188, v164, v189, v188
	v_fma_f32 v192, v164, v193, v192
	v_fma_f32 v188, v165, v190, v188
	v_fma_f32 v192, v165, v194, v192
	v_fma_f32 v188, v167, v191, v188
	v_fma_f32 v192, v167, v195, v192
	v_mul_f32 v196, v159, v196
	v_add_f32_dpp v188, v188, v188 row_half_mirror row_mask:0xf bank_mask:0x5
	v_add_f32_dpp v188, v192, v192 row_half_mirror row_mask:0xf bank_mask:0xa
	v_mul_f32 v197, v164, v197
	v_mul_f32 v198, v165, v198
	v_add_f32_dpp v188, v188, v188 quad_perm:[1,0,3,2] row_mask:0xf bank_mask:0xf
	v_mul_f32 v199, v167, v199
	v_fma_f32 v196, v208, v204, v196
	v_add_f32_dpp v188, v188, v188 quad_perm:[2,3,0,1] row_mask:0xf bank_mask:0xf
	v_fma_f32 v197, v208, v205, v197
	v_fma_f32 v198, v208, v206, v198
	v_add_f32_dpp v188, v188, v188 row_ror:8 row_mask:0xf bank_mask:0xf
	v_fma_f32 v199, v208, v207, v199
	v_fma_f32 v192, v208, v210, v188
	v_mov_b32_dpp v188, v188 row_half_mirror row_mask:0xf bank_mask:0xa
	ds_read_b128 v[204:207], v3 offset:14848
	v_fma_f32 v159, -v188, v200, v196
	v_fma_f32 v164, -v188, v201, v197
	v_fma_f32 v165, -v188, v202, v198
	v_fma_f32 v167, -v188, v203, v199
	v_fma_f32 v192, -v188, v209, v192
	ds_read_b128 v[188:191], v3 offset:13824
	ds_write_b32 v2, v192 offset:448
	ds_read_b128 v[192:195], v3 offset:14080
	ds_read_b128 v[196:199], v3 offset:14336
	ds_read_b128 v[208:211], v4 offset:13824
	ds_read_b128 v[200:203], v3 offset:14592
	s_waitcnt lgkmcnt(7)
	v_mul_f32 v160, v159, v160
	v_mul_f32 v168, v159, v168
	v_fma_f32 v160, v164, v161, v160
	v_fma_f32 v168, v164, v169, v168
	v_fma_f32 v160, v165, v162, v160
	v_fma_f32 v168, v165, v170, v168
	v_fma_f32 v160, v167, v163, v160
	v_fma_f32 v168, v167, v171, v168
	v_mul_f32 v172, v159, v172
	v_add_f32_dpp v160, v160, v160 row_half_mirror row_mask:0xf bank_mask:0x5
	v_add_f32_dpp v160, v168, v168 row_half_mirror row_mask:0xf bank_mask:0xa
	v_mul_f32 v173, v164, v173
	v_mul_f32 v174, v165, v174
	v_add_f32_dpp v160, v160, v160 quad_perm:[1,0,3,2] row_mask:0xf bank_mask:0xf
	v_mul_f32 v175, v167, v175
	v_fma_f32 v172, v184, v180, v172
	v_add_f32_dpp v160, v160, v160 quad_perm:[2,3,0,1] row_mask:0xf bank_mask:0xf
	v_fma_f32 v173, v184, v181, v173
	v_fma_f32 v174, v184, v182, v174
	v_add_f32_dpp v160, v160, v160 row_ror:8 row_mask:0xf bank_mask:0xf
	v_fma_f32 v175, v184, v183, v175
	v_fma_f32 v168, v184, v186, v160
	v_mov_b32_dpp v160, v160 row_half_mirror row_mask:0xf bank_mask:0xa
	ds_read_b128 v[180:183], v3 offset:16384
	v_fma_f32 v159, -v160, v176, v172
	v_fma_f32 v164, -v160, v177, v173
	v_fma_f32 v165, -v160, v178, v174
	v_fma_f32 v167, -v160, v179, v175
	v_fma_f32 v168, -v160, v185, v168
	ds_read_b128 v[160:163], v3 offset:15360
	ds_write_b32 v2, v168 offset:512
	ds_read_b128 v[168:171], v3 offset:15616
	ds_read_b128 v[172:175], v3 offset:15872
	ds_read_b128 v[184:187], v4 offset:15360
	ds_read_b128 v[176:179], v3 offset:16128
	s_waitcnt lgkmcnt(7)
	v_mul_f32 v188, v159, v188
	v_mul_f32 v192, v159, v192
	v_fma_f32 v188, v164, v189, v188
	v_fma_f32 v192, v164, v193, v192
	v_fma_f32 v188, v165, v190, v188
	v_fma_f32 v192, v165, v194, v192
	v_fma_f32 v188, v167, v191, v188
	v_fma_f32 v192, v167, v195, v192
	v_mul_f32 v196, v159, v196
	v_add_f32_dpp v188, v188, v188 row_half_mirror row_mask:0xf bank_mask:0x5
	v_add_f32_dpp v188, v192, v192 row_half_mirror row_mask:0xf bank_mask:0xa
	v_mul_f32 v197, v164, v197
	v_mul_f32 v198, v165, v198
	v_add_f32_dpp v188, v188, v188 quad_perm:[1,0,3,2] row_mask:0xf bank_mask:0xf
	v_mul_f32 v199, v167, v199
	v_fma_f32 v196, v208, v204, v196
	v_add_f32_dpp v188, v188, v188 quad_perm:[2,3,0,1] row_mask:0xf bank_mask:0xf
	v_fma_f32 v197, v208, v205, v197
	v_fma_f32 v198, v208, v206, v198
	v_add_f32_dpp v188, v188, v188 row_ror:8 row_mask:0xf bank_mask:0xf
	v_fma_f32 v199, v208, v207, v199
	v_fma_f32 v192, v208, v210, v188
	v_mov_b32_dpp v188, v188 row_half_mirror row_mask:0xf bank_mask:0xa
	ds_read_b128 v[204:207], v3 offset:17920
	v_fma_f32 v159, -v188, v200, v196
	v_fma_f32 v164, -v188, v201, v197
	v_fma_f32 v165, -v188, v202, v198
	v_fma_f32 v167, -v188, v203, v199
	v_fma_f32 v192, -v188, v209, v192
	ds_read_b128 v[188:191], v3 offset:16896
	ds_write_b32 v2, v192 offset:576
	ds_read_b128 v[192:195], v3 offset:17152
	ds_read_b128 v[196:199], v3 offset:17408
	ds_read_b128 v[208:211], v4 offset:16896
	ds_read_b128 v[200:203], v3 offset:17664
	s_waitcnt lgkmcnt(7)
	v_mul_f32 v160, v159, v160
	v_mul_f32 v168, v159, v168
	v_fma_f32 v160, v164, v161, v160
	v_fma_f32 v168, v164, v169, v168
	v_fma_f32 v160, v165, v162, v160
	v_fma_f32 v168, v165, v170, v168
	v_fma_f32 v160, v167, v163, v160
	v_fma_f32 v168, v167, v171, v168
	v_mul_f32 v172, v159, v172
	v_add_f32_dpp v160, v160, v160 row_half_mirror row_mask:0xf bank_mask:0x5
	v_add_f32_dpp v160, v168, v168 row_half_mirror row_mask:0xf bank_mask:0xa
	v_mul_f32 v173, v164, v173
	v_mul_f32 v174, v165, v174
	v_add_f32_dpp v160, v160, v160 quad_perm:[1,0,3,2] row_mask:0xf bank_mask:0xf
	v_mul_f32 v175, v167, v175
	v_fma_f32 v172, v184, v180, v172
	v_add_f32_dpp v160, v160, v160 quad_perm:[2,3,0,1] row_mask:0xf bank_mask:0xf
	v_fma_f32 v173, v184, v181, v173
	v_fma_f32 v174, v184, v182, v174
	v_add_f32_dpp v160, v160, v160 row_ror:8 row_mask:0xf bank_mask:0xf
	v_fma_f32 v175, v184, v183, v175
	v_fma_f32 v168, v184, v186, v160
	v_mov_b32_dpp v160, v160 row_half_mirror row_mask:0xf bank_mask:0xa
	ds_read_b128 v[180:183], v3 offset:19456
	v_fma_f32 v159, -v160, v176, v172
	v_fma_f32 v164, -v160, v177, v173
	v_fma_f32 v165, -v160, v178, v174
	v_fma_f32 v167, -v160, v179, v175
	v_fma_f32 v168, -v160, v185, v168
	ds_read_b128 v[160:163], v3 offset:18432
	ds_write_b32 v2, v168 offset:640
	ds_read_b128 v[168:171], v3 offset:18688
	ds_read_b128 v[172:175], v3 offset:18944
	ds_read_b128 v[184:187], v4 offset:18432
	ds_read_b128 v[176:179], v3 offset:19200
	s_waitcnt lgkmcnt(7)
; __device__ __forceinline__ float vfma(float a, float b, float c) { float d; asm("v_fma_f32 %0, %1, %2, %3" : "=v"(d) : "v"(a), "v"(b), "v"(c)); return d; }
; __device__ __forceinline__ float vnfma(float a, float b, float c) { float d; asm("v_fma_f32 %0, -%1, %2, %3" : "=v"(d) : "v"(a), "v"(b), "v"(c)); return d; }
; __device__ __forceinline__ float vmul(float a, float b) { float d; asm("v_mul_f32 %0, %1, %2" : "=v"(d) : "v"(a), "v"(b)); return d; }
; __device__ __forceinline__ float vadd(float a, float b) { float d; asm("v_add_f32 %0, %1, %2" : "=v"(d) : "v"(a), "v"(b)); return d; }
; __device__ __forceinline__ float step_compute(float (&S)[4], const StepOp& o) {
;     float d1 = vmul(S[0], o.kk[0]), d2 = vmul(S[0], o.wr[0]), e1 = vmul(S[1], o.kk[1]), e2 = vmul(S[1], o.wr[1]);
;     d1 = vfma(S[2], o.kk[2], d1); d2 = vfma(S[2], o.wr[2], d2); e1 = vfma(S[3], o.kk[3], e1); e2 = vfma(S[3], o.wr[3], e2);
;     d1 = vadd(d1, e1); d2 = vadd(d2, e2);
;     float t0, t1, t2, t3;
;     asm volatile(
;         "v_mul_f32 %[t0], %[s0], %[w0]\n\t"
;         "v_mul_f32 %[t1], %[s1], %[w1]\n\t"
;         "v_add_f32_dpp %[d1], %[d1], %[d1] quad_perm:[1,0,3,2] row_mask:0xf bank_mask:0xf bound_ctrl:1\n\t"
;         "v_add_f32_dpp %[d2], %[d2], %[d2] quad_perm:[1,0,3,2] row_mask:0xf bank_mask:0xf bound_ctrl:1\n\t"
;         "v_mul_f32 %[t2], %[s2], %[w2]\n\t"
;         "v_add_f32_dpp %[d1], %[d1], %[d1] quad_perm:[2,3,0,1] row_mask:0xf bank_mask:0xf bound_ctrl:1\n\t"
;         "v_add_f32_dpp %[d2], %[d2], %[d2] quad_perm:[2,3,0,1] row_mask:0xf bank_mask:0xf bound_ctrl:1\n\t"
;         "v_mul_f32 %[t3], %[s3], %[w3]\n\t"
;         "v_add_f32_dpp %[d1], %[d1], %[d1] row_half_mirror row_mask:0xf bank_mask:0xf bound_ctrl:1\n\t"
;         "v_add_f32_dpp %[d2], %[d2], %[d2] row_half_mirror row_mask:0xf bank_mask:0xf bound_ctrl:1\n\t"
;         "v_fma_f32 %[t0], %[v], %[k0], %[t0]\n\t"
;         "v_add_f32_dpp %[d1], %[d1], %[d1] row_mirror row_mask:0xf bank_mask:0xf bound_ctrl:1\n\t"
;         "v_add_f32_dpp %[d2], %[d2], %[d2] row_mirror row_mask:0xf bank_mask:0xf bound_ctrl:1\n\t"
;         "v_fma_f32 %[t1], %[v], %[k1], %[t1]\n\t"
;         "v_fma_f32 %[t2], %[v], %[k2], %[t2]\n\t"
;         "v_fma_f32 %[t3], %[v], %[k3], %[t3]"
;         : [t0] "=&v"(t0), [t1] "=&v"(t1), [t2] "=&v"(t2), [t3] "=&v"(t3), [d1] "+v"(d1), [d2] "+v"(d2)
	v_mul_f32 v188, v159, v188
	v_mul_f32 v192, v159, v192
	v_fma_f32 v188, v164, v189, v188
	v_fma_f32 v192, v164, v193, v192
	v_fma_f32 v188, v165, v190, v188
	v_fma_f32 v192, v165, v194, v192
	v_fma_f32 v188, v167, v191, v188
	v_fma_f32 v192, v167, v195, v192
	v_mul_f32 v196, v159, v196
	v_add_f32_dpp v188, v188, v188 row_half_mirror row_mask:0xf bank_mask:0x5
	v_add_f32_dpp v188, v192, v192 row_half_mirror row_mask:0xf bank_mask:0xa
	v_mul_f32 v197, v164, v197
	v_mul_f32 v198, v165, v198
	v_add_f32_dpp v188, v188, v188 quad_perm:[1,0,3,2] row_mask:0xf bank_mask:0xf
	v_mul_f32 v199, v167, v199
	v_fma_f32 v196, v208, v204, v196
	v_add_f32_dpp v188, v188, v188 quad_perm:[2,3,0,1] row_mask:0xf bank_mask:0xf
	v_fma_f32 v197, v208, v205, v197
	v_fma_f32 v198, v208, v206, v198
	v_add_f32_dpp v188, v188, v188 row_ror:8 row_mask:0xf bank_mask:0xf
	v_fma_f32 v199, v208, v207, v199
	v_fma_f32 v192, v208, v210, v188
	v_mov_b32_dpp v188, v188 row_half_mirror row_mask:0xf bank_mask:0xa
	ds_read_b128 v[204:207], v3 offset:20992
	v_fma_f32 v159, -v188, v200, v196
	v_fma_f32 v164, -v188, v201, v197
	v_fma_f32 v165, -v188, v202, v198
	v_fma_f32 v167, -v188, v203, v199
	v_fma_f32 v192, -v188, v209, v192
	ds_read_b128 v[188:191], v3 offset:19968
	ds_write_b32 v2, v192 offset:704
	ds_read_b128 v[192:195], v3 offset:20224
	ds_read_b128 v[196:199], v3 offset:20480
	ds_read_b128 v[208:211], v4 offset:19968
	ds_read_b128 v[200:203], v3 offset:20736
	s_waitcnt lgkmcnt(7)
	v_mul_f32 v160, v159, v160
	v_mul_f32 v168, v159, v168
	v_fma_f32 v160, v164, v161, v160
	v_fma_f32 v168, v164, v169, v168
	v_fma_f32 v160, v165, v162, v160
	v_fma_f32 v168, v165, v170, v168
	v_fma_f32 v160, v167, v163, v160
	v_fma_f32 v168, v167, v171, v168
	v_mul_f32 v172, v159, v172
	v_add_f32_dpp v160, v160, v160 row_half_mirror row_mask:0xf bank_mask:0x5
	v_add_f32_dpp v160, v168, v168 row_half_mirror row_mask:0xf bank_mask:0xa
	v_mul_f32 v173, v164, v173
	v_mul_f32 v174, v165, v174
	v_add_f32_dpp v160, v160, v160 quad_perm:[1,0,3,2] row_mask:0xf bank_mask:0xf
	v_mul_f32 v175, v167, v175
	v_fma_f32 v172, v184, v180, v172
	v_add_f32_dpp v160, v160, v160 quad_perm:[2,3,0,1] row_mask:0xf bank_mask:0xf
	v_fma_f32 v173, v184, v181, v173
	v_fma_f32 v174, v184, v182, v174
	v_add_f32_dpp v160, v160, v160 row_ror:8 row_mask:0xf bank_mask:0xf
	v_fma_f32 v175, v184, v183, v175
	v_fma_f32 v168, v184, v186, v160
	v_mov_b32_dpp v160, v160 row_half_mirror row_mask:0xf bank_mask:0xa
	ds_read_b128 v[180:183], v3 offset:22528
	v_fma_f32 v159, -v160, v176, v172
	v_fma_f32 v164, -v160, v177, v173
	v_fma_f32 v165, -v160, v178, v174
	v_fma_f32 v167, -v160, v179, v175
	v_fma_f32 v168, -v160, v185, v168
	ds_read_b128 v[160:163], v3 offset:21504
	ds_write_b32 v2, v168 offset:768
	ds_read_b128 v[168:171], v3 offset:21760
	ds_read_b128 v[172:175], v3 offset:22016
	ds_read_b128 v[184:187], v4 offset:21504
	ds_read_b128 v[176:179], v3 offset:22272
	s_waitcnt lgkmcnt(7)
	v_mul_f32 v188, v159, v188
	v_mul_f32 v192, v159, v192
	v_fma_f32 v188, v164, v189, v188
	v_fma_f32 v192, v164, v193, v192
	v_fma_f32 v188, v165, v190, v188
	v_fma_f32 v192, v165, v194, v192
	v_fma_f32 v188, v167, v191, v188
	v_fma_f32 v192, v167, v195, v192
	v_mul_f32 v196, v159, v196
	v_add_f32_dpp v188, v188, v188 row_half_mirror row_mask:0xf bank_mask:0x5
	v_add_f32_dpp v188, v192, v192 row_half_mirror row_mask:0xf bank_mask:0xa
	v_mul_f32 v197, v164, v197
	v_mul_f32 v198, v165, v198
	v_add_f32_dpp v188, v188, v188 quad_perm:[1,0,3,2] row_mask:0xf bank_mask:0xf
	v_mul_f32 v199, v167, v199
	v_fma_f32 v196, v208, v204, v196
	v_add_f32_dpp v188, v188, v188 quad_perm:[2,3,0,1] row_mask:0xf bank_mask:0xf
	v_fma_f32 v197, v208, v205, v197
	v_fma_f32 v198, v208, v206, v198
	v_add_f32_dpp v188, v188, v188 row_ror:8 row_mask:0xf bank_mask:0xf
	v_fma_f32 v199, v208, v207, v199
	v_fma_f32 v192, v208, v210, v188
	v_mov_b32_dpp v188, v188 row_half_mirror row_mask:0xf bank_mask:0xa
	ds_read_b128 v[204:207], v3 offset:24064
	v_fma_f32 v159, -v188, v200, v196
	v_fma_f32 v164, -v188, v201, v197
	v_fma_f32 v165, -v188, v202, v198
	v_fma_f32 v167, -v188, v203, v199
	v_fma_f32 v192, -v188, v209, v192
	ds_read_b128 v[188:191], v3 offset:23040
	ds_write_b32 v2, v192 offset:832
	ds_read_b128 v[192:195], v3 offset:23296
	ds_read_b128 v[196:199], v3 offset:23552
	ds_read_b128 v[208:211], v4 offset:23040
	ds_read_b128 v[200:203], v3 offset:23808
	s_waitcnt lgkmcnt(7)
	v_mul_f32 v160, v159, v160
	v_mul_f32 v168, v159, v168
	v_fma_f32 v160, v164, v161, v160
	v_fma_f32 v168, v164, v169, v168
	v_fma_f32 v160, v165, v162, v160
	v_fma_f32 v168, v165, v170, v168
	v_fma_f32 v160, v167, v163, v160
	v_fma_f32 v168, v167, v171, v168
	v_mul_f32 v172, v159, v172
	v_add_f32_dpp v160, v160, v160 row_half_mirror row_mask:0xf bank_mask:0x5
	v_add_f32_dpp v160, v168, v168 row_half_mirror row_mask:0xf bank_mask:0xa
	v_mul_f32 v173, v164, v173
	v_mul_f32 v174, v165, v174
	v_add_f32_dpp v160, v160, v160 quad_perm:[1,0,3,2] row_mask:0xf bank_mask:0xf
	v_mul_f32 v175, v167, v175
	v_fma_f32 v172, v184, v180, v172
	v_add_f32_dpp v160, v160, v160 quad_perm:[2,3,0,1] row_mask:0xf bank_mask:0xf
	v_fma_f32 v173, v184, v181, v173
	v_fma_f32 v174, v184, v182, v174
	v_add_f32_dpp v160, v160, v160 row_ror:8 row_mask:0xf bank_mask:0xf
	v_fma_f32 v175, v184, v183, v175
	v_fma_f32 v168, v184, v186, v160
	v_mov_b32_dpp v160, v160 row_half_mirror row_mask:0xf bank_mask:0xa
	ds_read_b128 v[180:183], v3 offset:25600
	v_fma_f32 v159, -v160, v176, v172
	v_fma_f32 v164, -v160, v177, v173
	v_fma_f32 v165, -v160, v178, v174
	v_fma_f32 v167, -v160, v179, v175
	v_fma_f32 v168, -v160, v185, v168
	ds_read_b128 v[160:163], v3 offset:24576
	ds_write_b32 v2, v168 offset:896
	ds_read_b128 v[168:171], v3 offset:24832
	ds_read_b128 v[172:175], v3 offset:25088
	ds_read_b128 v[184:187], v4 offset:24576
	ds_read_b128 v[176:179], v3 offset:25344
	s_waitcnt lgkmcnt(7)
; __device__ __forceinline__ float vfma(float a, float b, float c) { float d; asm("v_fma_f32 %0, %1, %2, %3" : "=v"(d) : "v"(a), "v"(b), "v"(c)); return d; }
; __device__ __forceinline__ float vnfma(float a, float b, float c) { float d; asm("v_fma_f32 %0, -%1, %2, %3" : "=v"(d) : "v"(a), "v"(b), "v"(c)); return d; }
; __device__ __forceinline__ float vmul(float a, float b) { float d; asm("v_mul_f32 %0, %1, %2" : "=v"(d) : "v"(a), "v"(b)); return d; }
; __device__ __forceinline__ float vadd(float a, float b) { float d; asm("v_add_f32 %0, %1, %2" : "=v"(d) : "v"(a), "v"(b)); return d; }
; __device__ __forceinline__ float step_compute(float (&S)[4], const StepOp& o) {
;     float d1 = vmul(S[0], o.kk[0]), d2 = vmul(S[0], o.wr[0]), e1 = vmul(S[1], o.kk[1]), e2 = vmul(S[1], o.wr[1]);
;     d1 = vfma(S[2], o.kk[2], d1); d2 = vfma(S[2], o.wr[2], d2); e1 = vfma(S[3], o.kk[3], e1); e2 = vfma(S[3], o.wr[3], e2);
;     d1 = vadd(d1, e1); d2 = vadd(d2, e2);
;     float t0, t1, t2, t3;
;     asm volatile(
;         "v_mul_f32 %[t0], %[s0], %[w0]\n\t"
;         "v_mul_f32 %[t1], %[s1], %[w1]\n\t"
;         "v_add_f32_dpp %[d1], %[d1], %[d1] quad_perm:[1,0,3,2] row_mask:0xf bank_mask:0xf bound_ctrl:1\n\t"
;         "v_add_f32_dpp %[d2], %[d2], %[d2] quad_perm:[1,0,3,2] row_mask:0xf bank_mask:0xf bound_ctrl:1\n\t"
;         "v_mul_f32 %[t2], %[s2], %[w2]\n\t"
;         "v_add_f32_dpp %[d1], %[d1], %[d1] quad_perm:[2,3,0,1] row_mask:0xf bank_mask:0xf bound_ctrl:1\n\t"
;         "v_add_f32_dpp %[d2], %[d2], %[d2] quad_perm:[2,3,0,1] row_mask:0xf bank_mask:0xf bound_ctrl:1\n\t"
;         "v_mul_f32 %[t3], %[s3], %[w3]\n\t"
;         "v_add_f32_dpp %[d1], %[d1], %[d1] row_half_mirror row_mask:0xf bank_mask:0xf bound_ctrl:1\n\t"
;         "v_add_f32_dpp %[d2], %[d2], %[d2] row_half_mirror row_mask:0xf bank_mask:0xf bound_ctrl:1\n\t"
;         "v_fma_f32 %[t0], %[v], %[k0], %[t0]\n\t"
;         "v_add_f32_dpp %[d1], %[d1], %[d1] row_mirror row_mask:0xf bank_mask:0xf bound_ctrl:1\n\t"
;         "v_add_f32_dpp %[d2], %[d2], %[d2] row_mirror row_mask:0xf bank_mask:0xf bound_ctrl:1\n\t"
;         "v_fma_f32 %[t1], %[v], %[k1], %[t1]\n\t"
;         "v_fma_f32 %[t2], %[v], %[k2], %[t2]\n\t"
;         "v_fma_f32 %[t3], %[v], %[k3], %[t3]"
;         : [t0] "=&v"(t0), [t1] "=&v"(t1), [t2] "=&v"(t2), [t3] "=&v"(t3), [d1] "+v"(d1), [d2] "+v"(d2)
	v_mul_f32 v188, v159, v188
	v_mul_f32 v192, v159, v192
	v_fma_f32 v188, v164, v189, v188
	v_fma_f32 v192, v164, v193, v192
	v_fma_f32 v188, v165, v190, v188
	v_fma_f32 v192, v165, v194, v192
	v_fma_f32 v188, v167, v191, v188
	v_fma_f32 v192, v167, v195, v192
	v_mul_f32 v196, v159, v196
	v_add_f32_dpp v188, v188, v188 row_half_mirror row_mask:0xf bank_mask:0x5
	v_add_f32_dpp v188, v192, v192 row_half_mirror row_mask:0xf bank_mask:0xa
	v_mul_f32 v197, v164, v197
	v_mul_f32 v198, v165, v198
	v_add_f32_dpp v188, v188, v188 quad_perm:[1,0,3,2] row_mask:0xf bank_mask:0xf
	v_mul_f32 v199, v167, v199
	v_fma_f32 v196, v208, v204, v196
	v_add_f32_dpp v188, v188, v188 quad_perm:[2,3,0,1] row_mask:0xf bank_mask:0xf
	v_fma_f32 v197, v208, v205, v197
	v_fma_f32 v198, v208, v206, v198
	v_add_f32_dpp v188, v188, v188 row_ror:8 row_mask:0xf bank_mask:0xf
	v_fma_f32 v199, v208, v207, v199
	v_fma_f32 v192, v208, v210, v188
	v_mov_b32_dpp v188, v188 row_half_mirror row_mask:0xf bank_mask:0xa
	ds_read_b128 v[204:207], v3 offset:27136
	v_fma_f32 v159, -v188, v200, v196
	v_fma_f32 v164, -v188, v201, v197
	v_fma_f32 v165, -v188, v202, v198
	v_fma_f32 v167, -v188, v203, v199
	v_fma_f32 v192, -v188, v209, v192
	ds_read_b128 v[188:191], v3 offset:26112
	ds_write_b32 v2, v192 offset:960
	ds_read_b128 v[192:195], v3 offset:26368
	ds_read_b128 v[196:199], v3 offset:26624
	ds_read_b128 v[208:211], v4 offset:26112
	ds_read_b128 v[200:203], v3 offset:26880
	s_waitcnt lgkmcnt(7)
	v_mul_f32 v160, v159, v160
	v_mul_f32 v168, v159, v168
	v_fma_f32 v160, v164, v161, v160
	v_fma_f32 v168, v164, v169, v168
	v_fma_f32 v160, v165, v162, v160
	v_fma_f32 v168, v165, v170, v168
	v_fma_f32 v160, v167, v163, v160
	v_fma_f32 v168, v167, v171, v168
	v_mul_f32 v172, v159, v172
	v_add_f32_dpp v160, v160, v160 row_half_mirror row_mask:0xf bank_mask:0x5
	v_add_f32_dpp v160, v168, v168 row_half_mirror row_mask:0xf bank_mask:0xa
	v_mul_f32 v173, v164, v173
	v_mul_f32 v174, v165, v174
	v_add_f32_dpp v160, v160, v160 quad_perm:[1,0,3,2] row_mask:0xf bank_mask:0xf
	v_mul_f32 v175, v167, v175
	v_fma_f32 v172, v184, v180, v172
	v_add_f32_dpp v160, v160, v160 quad_perm:[2,3,0,1] row_mask:0xf bank_mask:0xf
	v_fma_f32 v173, v184, v181, v173
	v_fma_f32 v174, v184, v182, v174
	v_add_f32_dpp v160, v160, v160 row_ror:8 row_mask:0xf bank_mask:0xf
	v_fma_f32 v175, v184, v183, v175
	v_fma_f32 v168, v184, v186, v160
	v_mov_b32_dpp v160, v160 row_half_mirror row_mask:0xf bank_mask:0xa
	ds_read_b128 v[180:183], v3 offset:28672
	v_fma_f32 v159, -v160, v176, v172
	v_fma_f32 v164, -v160, v177, v173
	v_fma_f32 v165, -v160, v178, v174
	v_fma_f32 v167, -v160, v179, v175
	v_fma_f32 v168, -v160, v185, v168
	ds_read_b128 v[160:163], v3 offset:27648
	ds_write_b32 v2, v168 offset:1024
	ds_read_b128 v[168:171], v3 offset:27904
	ds_read_b128 v[172:175], v3 offset:28160
	ds_read_b128 v[184:187], v4 offset:27648
	ds_read_b128 v[176:179], v3 offset:28416
	s_waitcnt lgkmcnt(7)
	v_mul_f32 v188, v159, v188
	v_mul_f32 v192, v159, v192
	v_fma_f32 v188, v164, v189, v188
	v_fma_f32 v192, v164, v193, v192
	v_fma_f32 v188, v165, v190, v188
	v_fma_f32 v192, v165, v194, v192
	v_fma_f32 v188, v167, v191, v188
	v_fma_f32 v192, v167, v195, v192
	v_mul_f32 v196, v159, v196
	v_add_f32_dpp v188, v188, v188 row_half_mirror row_mask:0xf bank_mask:0x5
	v_add_f32_dpp v188, v192, v192 row_half_mirror row_mask:0xf bank_mask:0xa
	v_mul_f32 v197, v164, v197
	v_mul_f32 v198, v165, v198
	v_add_f32_dpp v188, v188, v188 quad_perm:[1,0,3,2] row_mask:0xf bank_mask:0xf
	v_mul_f32 v199, v167, v199
	v_fma_f32 v196, v208, v204, v196
	v_add_f32_dpp v188, v188, v188 quad_perm:[2,3,0,1] row_mask:0xf bank_mask:0xf
	v_fma_f32 v197, v208, v205, v197
	v_fma_f32 v198, v208, v206, v198
	v_add_f32_dpp v188, v188, v188 row_ror:8 row_mask:0xf bank_mask:0xf
	v_fma_f32 v199, v208, v207, v199
	v_fma_f32 v192, v208, v210, v188
	v_mov_b32_dpp v188, v188 row_half_mirror row_mask:0xf bank_mask:0xa
	ds_read_b128 v[204:207], v3 offset:30208
	v_fma_f32 v159, -v188, v200, v196
	v_fma_f32 v164, -v188, v201, v197
	v_fma_f32 v165, -v188, v202, v198
	v_fma_f32 v167, -v188, v203, v199
	v_fma_f32 v192, -v188, v209, v192
	ds_read_b128 v[188:191], v3 offset:29184
	ds_write_b32 v2, v192 offset:1088
	ds_read_b128 v[192:195], v3 offset:29440
	ds_read_b128 v[196:199], v3 offset:29696
	ds_read_b128 v[208:211], v4 offset:29184
	ds_read_b128 v[200:203], v3 offset:29952
	s_waitcnt lgkmcnt(7)
	v_mul_f32 v160, v159, v160
	v_mul_f32 v168, v159, v168
	v_fma_f32 v160, v164, v161, v160
	v_fma_f32 v168, v164, v169, v168
	v_fma_f32 v160, v165, v162, v160
	v_fma_f32 v168, v165, v170, v168
	v_fma_f32 v160, v167, v163, v160
	v_fma_f32 v168, v167, v171, v168
	v_mul_f32 v172, v159, v172
	v_add_f32_dpp v160, v160, v160 row_half_mirror row_mask:0xf bank_mask:0x5
	v_add_f32_dpp v160, v168, v168 row_half_mirror row_mask:0xf bank_mask:0xa
	v_mul_f32 v173, v164, v173
	v_mul_f32 v174, v165, v174
	v_add_f32_dpp v160, v160, v160 quad_perm:[1,0,3,2] row_mask:0xf bank_mask:0xf
	v_mul_f32 v175, v167, v175
	v_fma_f32 v172, v184, v180, v172
	v_add_f32_dpp v160, v160, v160 quad_perm:[2,3,0,1] row_mask:0xf bank_mask:0xf
	v_fma_f32 v173, v184, v181, v173
	v_fma_f32 v174, v184, v182, v174
	v_add_f32_dpp v160, v160, v160 row_ror:8 row_mask:0xf bank_mask:0xf
	v_fma_f32 v175, v184, v183, v175
	v_fma_f32 v168, v184, v186, v160
	v_mov_b32_dpp v160, v160 row_half_mirror row_mask:0xf bank_mask:0xa
	ds_read_b128 v[180:183], v3 offset:31744
	v_fma_f32 v159, -v160, v176, v172
	v_fma_f32 v164, -v160, v177, v173
	v_fma_f32 v165, -v160, v178, v174
	v_fma_f32 v167, -v160, v179, v175
	v_fma_f32 v168, -v160, v185, v168
	ds_read_b128 v[160:163], v3 offset:30720
	ds_write_b32 v2, v168 offset:1152
	ds_read_b128 v[168:171], v3 offset:30976
	ds_read_b128 v[172:175], v3 offset:31232
	ds_read_b128 v[184:187], v4 offset:30720
	ds_read_b128 v[176:179], v3 offset:31488
	s_waitcnt lgkmcnt(7)
; __device__ __forceinline__ float vfma(float a, float b, float c) { float d; asm("v_fma_f32 %0, %1, %2, %3" : "=v"(d) : "v"(a), "v"(b), "v"(c)); return d; }
; __device__ __forceinline__ float vnfma(float a, float b, float c) { float d; asm("v_fma_f32 %0, -%1, %2, %3" : "=v"(d) : "v"(a), "v"(b), "v"(c)); return d; }
; __device__ __forceinline__ float vmul(float a, float b) { float d; asm("v_mul_f32 %0, %1, %2" : "=v"(d) : "v"(a), "v"(b)); return d; }
; __device__ __forceinline__ float vadd(float a, float b) { float d; asm("v_add_f32 %0, %1, %2" : "=v"(d) : "v"(a), "v"(b)); return d; }
; __device__ __forceinline__ float step_compute(float (&S)[4], const StepOp& o) {
;     float d1 = vmul(S[0], o.kk[0]), d2 = vmul(S[0], o.wr[0]), e1 = vmul(S[1], o.kk[1]), e2 = vmul(S[1], o.wr[1]);
;     d1 = vfma(S[2], o.kk[2], d1); d2 = vfma(S[2], o.wr[2], d2); e1 = vfma(S[3], o.kk[3], e1); e2 = vfma(S[3], o.wr[3], e2);
;     d1 = vadd(d1, e1); d2 = vadd(d2, e2);
;     float t0, t1, t2, t3;
;     asm volatile(
;         "v_mul_f32 %[t0], %[s0], %[w0]\n\t"
;         "v_mul_f32 %[t1], %[s1], %[w1]\n\t"
;         "v_add_f32_dpp %[d1], %[d1], %[d1] quad_perm:[1,0,3,2] row_mask:0xf bank_mask:0xf bound_ctrl:1\n\t"
;         "v_add_f32_dpp %[d2], %[d2], %[d2] quad_perm:[1,0,3,2] row_mask:0xf bank_mask:0xf bound_ctrl:1\n\t"
;         "v_mul_f32 %[t2], %[s2], %[w2]\n\t"
;         "v_add_f32_dpp %[d1], %[d1], %[d1] quad_perm:[2,3,0,1] row_mask:0xf bank_mask:0xf bound_ctrl:1\n\t"
;         "v_add_f32_dpp %[d2], %[d2], %[d2] quad_perm:[2,3,0,1] row_mask:0xf bank_mask:0xf bound_ctrl:1\n\t"
;         "v_mul_f32 %[t3], %[s3], %[w3]\n\t"
;         "v_add_f32_dpp %[d1], %[d1], %[d1] row_half_mirror row_mask:0xf bank_mask:0xf bound_ctrl:1\n\t"
;         "v_add_f32_dpp %[d2], %[d2], %[d2] row_half_mirror row_mask:0xf bank_mask:0xf bound_ctrl:1\n\t"
;         "v_fma_f32 %[t0], %[v], %[k0], %[t0]\n\t"
;         "v_add_f32_dpp %[d1], %[d1], %[d1] row_mirror row_mask:0xf bank_mask:0xf bound_ctrl:1\n\t"
;         "v_add_f32_dpp %[d2], %[d2], %[d2] row_mirror row_mask:0xf bank_mask:0xf bound_ctrl:1\n\t"
;         "v_fma_f32 %[t1], %[v], %[k1], %[t1]\n\t"
;         "v_fma_f32 %[t2], %[v], %[k2], %[t2]\n\t"
;         "v_fma_f32 %[t3], %[v], %[k3], %[t3]"
;         : [t0] "=&v"(t0), [t1] "=&v"(t1), [t2] "=&v"(t2), [t3] "=&v"(t3), [d1] "+v"(d1), [d2] "+v"(d2)
	v_mul_f32 v188, v159, v188
	v_mul_f32 v192, v159, v192
	v_fma_f32 v188, v164, v189, v188
	v_fma_f32 v192, v164, v193, v192
	v_fma_f32 v188, v165, v190, v188
	v_fma_f32 v192, v165, v194, v192
	v_fma_f32 v188, v167, v191, v188
	v_fma_f32 v192, v167, v195, v192
	v_mul_f32 v196, v159, v196
	v_add_f32_dpp v188, v188, v188 row_half_mirror row_mask:0xf bank_mask:0x5
	v_add_f32_dpp v188, v192, v192 row_half_mirror row_mask:0xf bank_mask:0xa
	v_mul_f32 v197, v164, v197
	v_mul_f32 v198, v165, v198
	v_add_f32_dpp v188, v188, v188 quad_perm:[1,0,3,2] row_mask:0xf bank_mask:0xf
	v_mul_f32 v199, v167, v199
	v_fma_f32 v196, v208, v204, v196
	v_add_f32_dpp v188, v188, v188 quad_perm:[2,3,0,1] row_mask:0xf bank_mask:0xf
	v_fma_f32 v197, v208, v205, v197
	v_fma_f32 v198, v208, v206, v198
	v_add_f32_dpp v188, v188, v188 row_ror:8 row_mask:0xf bank_mask:0xf
	v_fma_f32 v199, v208, v207, v199
	v_fma_f32 v192, v208, v210, v188
	v_mov_b32_dpp v188, v188 row_half_mirror row_mask:0xf bank_mask:0xa
	ds_read_b128 v[204:207], v3 offset:33280
	v_fma_f32 v159, -v188, v200, v196
	v_fma_f32 v164, -v188, v201, v197
	v_fma_f32 v165, -v188, v202, v198
	v_fma_f32 v167, -v188, v203, v199
	v_fma_f32 v192, -v188, v209, v192
	ds_read_b128 v[188:191], v3 offset:32256
	ds_write_b32 v2, v192 offset:1216
	ds_read_b128 v[192:195], v3 offset:32512
	ds_read_b128 v[196:199], v3 offset:32768
	ds_read_b128 v[208:211], v4 offset:32256
	ds_read_b128 v[200:203], v3 offset:33024
	s_waitcnt lgkmcnt(7)
	v_mul_f32 v160, v159, v160
	v_mul_f32 v168, v159, v168
	v_fma_f32 v160, v164, v161, v160
	v_fma_f32 v168, v164, v169, v168
	v_fma_f32 v160, v165, v162, v160
	v_fma_f32 v168, v165, v170, v168
	v_fma_f32 v160, v167, v163, v160
	v_fma_f32 v168, v167, v171, v168
	v_mul_f32 v172, v159, v172
	v_add_f32_dpp v160, v160, v160 row_half_mirror row_mask:0xf bank_mask:0x5
	v_add_f32_dpp v160, v168, v168 row_half_mirror row_mask:0xf bank_mask:0xa
	v_mul_f32 v173, v164, v173
	v_mul_f32 v174, v165, v174
	v_add_f32_dpp v160, v160, v160 quad_perm:[1,0,3,2] row_mask:0xf bank_mask:0xf
	v_mul_f32 v175, v167, v175
	v_fma_f32 v172, v184, v180, v172
	v_add_f32_dpp v160, v160, v160 quad_perm:[2,3,0,1] row_mask:0xf bank_mask:0xf
	v_fma_f32 v173, v184, v181, v173
	v_fma_f32 v174, v184, v182, v174
	v_add_f32_dpp v160, v160, v160 row_ror:8 row_mask:0xf bank_mask:0xf
	v_fma_f32 v175, v184, v183, v175
	v_fma_f32 v168, v184, v186, v160
	v_mov_b32_dpp v160, v160 row_half_mirror row_mask:0xf bank_mask:0xa
	ds_read_b128 v[180:183], v3 offset:34816
	v_fma_f32 v159, -v160, v176, v172
	v_fma_f32 v164, -v160, v177, v173
	v_fma_f32 v165, -v160, v178, v174
	v_fma_f32 v167, -v160, v179, v175
	v_fma_f32 v168, -v160, v185, v168
	ds_read_b128 v[160:163], v3 offset:33792
	ds_write_b32 v2, v168 offset:1280
	ds_read_b128 v[168:171], v3 offset:34048
	ds_read_b128 v[172:175], v3 offset:34304
	ds_read_b128 v[184:187], v4 offset:33792
	ds_read_b128 v[176:179], v3 offset:34560
	s_waitcnt lgkmcnt(7)
	v_mul_f32 v188, v159, v188
	v_mul_f32 v192, v159, v192
	v_fma_f32 v188, v164, v189, v188
	v_fma_f32 v192, v164, v193, v192
	v_fma_f32 v188, v165, v190, v188
	v_fma_f32 v192, v165, v194, v192
	v_fma_f32 v188, v167, v191, v188
	v_fma_f32 v192, v167, v195, v192
	v_mul_f32 v196, v159, v196
	v_add_f32_dpp v188, v188, v188 row_half_mirror row_mask:0xf bank_mask:0x5
	v_add_f32_dpp v188, v192, v192 row_half_mirror row_mask:0xf bank_mask:0xa
	v_mul_f32 v197, v164, v197
	v_mul_f32 v198, v165, v198
	v_add_f32_dpp v188, v188, v188 quad_perm:[1,0,3,2] row_mask:0xf bank_mask:0xf
	v_mul_f32 v199, v167, v199
	v_fma_f32 v196, v208, v204, v196
	v_add_f32_dpp v188, v188, v188 quad_perm:[2,3,0,1] row_mask:0xf bank_mask:0xf
	v_fma_f32 v197, v208, v205, v197
	v_fma_f32 v198, v208, v206, v198
	v_add_f32_dpp v188, v188, v188 row_ror:8 row_mask:0xf bank_mask:0xf
	v_fma_f32 v199, v208, v207, v199
	v_fma_f32 v192, v208, v210, v188
	v_mov_b32_dpp v188, v188 row_half_mirror row_mask:0xf bank_mask:0xa
	ds_read_b128 v[204:207], v3 offset:36352
	v_fma_f32 v159, -v188, v200, v196
	v_fma_f32 v164, -v188, v201, v197
	v_fma_f32 v165, -v188, v202, v198
	v_fma_f32 v167, -v188, v203, v199
	v_fma_f32 v192, -v188, v209, v192
	ds_read_b128 v[188:191], v3 offset:35328
	ds_write_b32 v2, v192 offset:1344
	ds_read_b128 v[192:195], v3 offset:35584
	ds_read_b128 v[196:199], v3 offset:35840
	ds_read_b128 v[208:211], v4 offset:35328
	ds_read_b128 v[200:203], v3 offset:36096
	s_waitcnt lgkmcnt(7)
	v_mul_f32 v160, v159, v160
	v_mul_f32 v168, v159, v168
	v_fma_f32 v160, v164, v161, v160
	v_fma_f32 v168, v164, v169, v168
	v_fma_f32 v160, v165, v162, v160
	v_fma_f32 v168, v165, v170, v168
	v_fma_f32 v160, v167, v163, v160
	v_fma_f32 v168, v167, v171, v168
	v_mul_f32 v172, v159, v172
	v_add_f32_dpp v160, v160, v160 row_half_mirror row_mask:0xf bank_mask:0x5
	v_add_f32_dpp v160, v168, v168 row_half_mirror row_mask:0xf bank_mask:0xa
	v_mul_f32 v173, v164, v173
	v_mul_f32 v174, v165, v174
	v_add_f32_dpp v160, v160, v160 quad_perm:[1,0,3,2] row_mask:0xf bank_mask:0xf
	v_mul_f32 v175, v167, v175
	v_fma_f32 v172, v184, v180, v172
	v_add_f32_dpp v160, v160, v160 quad_perm:[2,3,0,1] row_mask:0xf bank_mask:0xf
	v_fma_f32 v173, v184, v181, v173
	v_fma_f32 v174, v184, v182, v174
	v_add_f32_dpp v160, v160, v160 row_ror:8 row_mask:0xf bank_mask:0xf
	v_fma_f32 v175, v184, v183, v175
	v_fma_f32 v168, v184, v186, v160
	v_mov_b32_dpp v160, v160 row_half_mirror row_mask:0xf bank_mask:0xa
	ds_read_b128 v[180:183], v3 offset:37888
	v_fma_f32 v159, -v160, v176, v172
	v_fma_f32 v164, -v160, v177, v173
	v_fma_f32 v165, -v160, v178, v174
	v_fma_f32 v167, -v160, v179, v175
	v_fma_f32 v168, -v160, v185, v168
	ds_read_b128 v[160:163], v3 offset:36864
	ds_write_b32 v2, v168 offset:1408
	ds_read_b128 v[168:171], v3 offset:37120
	ds_read_b128 v[172:175], v3 offset:37376
	ds_read_b128 v[184:187], v4 offset:36864
	ds_read_b128 v[176:179], v3 offset:37632
	s_waitcnt lgkmcnt(7)
; __device__ __forceinline__ float vfma(float a, float b, float c) { float d; asm("v_fma_f32 %0, %1, %2, %3" : "=v"(d) : "v"(a), "v"(b), "v"(c)); return d; }
; __device__ __forceinline__ float vnfma(float a, float b, float c) { float d; asm("v_fma_f32 %0, -%1, %2, %3" : "=v"(d) : "v"(a), "v"(b), "v"(c)); return d; }
; __device__ __forceinline__ float vmul(float a, float b) { float d; asm("v_mul_f32 %0, %1, %2" : "=v"(d) : "v"(a), "v"(b)); return d; }
; __device__ __forceinline__ float vadd(float a, float b) { float d; asm("v_add_f32 %0, %1, %2" : "=v"(d) : "v"(a), "v"(b)); return d; }
; __device__ __forceinline__ float step_compute(float (&S)[4], const StepOp& o) {
;     float d1 = vmul(S[0], o.kk[0]), d2 = vmul(S[0], o.wr[0]), e1 = vmul(S[1], o.kk[1]), e2 = vmul(S[1], o.wr[1]);
;     d1 = vfma(S[2], o.kk[2], d1); d2 = vfma(S[2], o.wr[2], d2); e1 = vfma(S[3], o.kk[3], e1); e2 = vfma(S[3], o.wr[3], e2);
;     d1 = vadd(d1, e1); d2 = vadd(d2, e2);
;     float t0, t1, t2, t3;
;     asm volatile(
;         "v_mul_f32 %[t0], %[s0], %[w0]\n\t"
;         "v_mul_f32 %[t1], %[s1], %[w1]\n\t"
;         "v_add_f32_dpp %[d1], %[d1], %[d1] quad_perm:[1,0,3,2] row_mask:0xf bank_mask:0xf bound_ctrl:1\n\t"
;         "v_add_f32_dpp %[d2], %[d2], %[d2] quad_perm:[1,0,3,2] row_mask:0xf bank_mask:0xf bound_ctrl:1\n\t"
;         "v_mul_f32 %[t2], %[s2], %[w2]\n\t"
;         "v_add_f32_dpp %[d1], %[d1], %[d1] quad_perm:[2,3,0,1] row_mask:0xf bank_mask:0xf bound_ctrl:1\n\t"
;         "v_add_f32_dpp %[d2], %[d2], %[d2] quad_perm:[2,3,0,1] row_mask:0xf bank_mask:0xf bound_ctrl:1\n\t"
;         "v_mul_f32 %[t3], %[s3], %[w3]\n\t"
;         "v_add_f32_dpp %[d1], %[d1], %[d1] row_half_mirror row_mask:0xf bank_mask:0xf bound_ctrl:1\n\t"
;         "v_add_f32_dpp %[d2], %[d2], %[d2] row_half_mirror row_mask:0xf bank_mask:0xf bound_ctrl:1\n\t"
;         "v_fma_f32 %[t0], %[v], %[k0], %[t0]\n\t"
;         "v_add_f32_dpp %[d1], %[d1], %[d1] row_mirror row_mask:0xf bank_mask:0xf bound_ctrl:1\n\t"
;         "v_add_f32_dpp %[d2], %[d2], %[d2] row_mirror row_mask:0xf bank_mask:0xf bound_ctrl:1\n\t"
;         "v_fma_f32 %[t1], %[v], %[k1], %[t1]\n\t"
;         "v_fma_f32 %[t2], %[v], %[k2], %[t2]\n\t"
;         "v_fma_f32 %[t3], %[v], %[k3], %[t3]"
;         : [t0] "=&v"(t0), [t1] "=&v"(t1), [t2] "=&v"(t2), [t3] "=&v"(t3), [d1] "+v"(d1), [d2] "+v"(d2)
	v_mul_f32 v188, v159, v188
	v_mul_f32 v192, v159, v192
	v_fma_f32 v188, v164, v189, v188
	v_fma_f32 v192, v164, v193, v192
	v_fma_f32 v188, v165, v190, v188
	v_fma_f32 v192, v165, v194, v192
	v_fma_f32 v188, v167, v191, v188
	v_fma_f32 v192, v167, v195, v192
	v_mul_f32 v196, v159, v196
	v_add_f32_dpp v188, v188, v188 row_half_mirror row_mask:0xf bank_mask:0x5
	v_add_f32_dpp v188, v192, v192 row_half_mirror row_mask:0xf bank_mask:0xa
	v_mul_f32 v197, v164, v197
	v_mul_f32 v198, v165, v198
	v_add_f32_dpp v188, v188, v188 quad_perm:[1,0,3,2] row_mask:0xf bank_mask:0xf
	v_mul_f32 v199, v167, v199
	v_fma_f32 v196, v208, v204, v196
	v_add_f32_dpp v188, v188, v188 quad_perm:[2,3,0,1] row_mask:0xf bank_mask:0xf
	v_fma_f32 v197, v208, v205, v197
	v_fma_f32 v198, v208, v206, v198
	v_add_f32_dpp v188, v188, v188 row_ror:8 row_mask:0xf bank_mask:0xf
	v_fma_f32 v199, v208, v207, v199
	v_fma_f32 v192, v208, v210, v188
	v_mov_b32_dpp v188, v188 row_half_mirror row_mask:0xf bank_mask:0xa
	ds_read_b128 v[204:207], v3 offset:39424
	v_fma_f32 v159, -v188, v200, v196
	v_fma_f32 v164, -v188, v201, v197
	v_fma_f32 v165, -v188, v202, v198
	v_fma_f32 v167, -v188, v203, v199
	v_fma_f32 v192, -v188, v209, v192
	ds_read_b128 v[188:191], v3 offset:38400
	ds_write_b32 v2, v192 offset:1472
	ds_read_b128 v[192:195], v3 offset:38656
	ds_read_b128 v[196:199], v3 offset:38912
	ds_read_b128 v[208:211], v4 offset:38400
	ds_read_b128 v[200:203], v3 offset:39168
	s_waitcnt lgkmcnt(7)
	v_mul_f32 v160, v159, v160
	v_mul_f32 v168, v159, v168
	v_fma_f32 v160, v164, v161, v160
	v_fma_f32 v168, v164, v169, v168
	v_fma_f32 v160, v165, v162, v160
	v_fma_f32 v168, v165, v170, v168
	v_fma_f32 v160, v167, v163, v160
	v_fma_f32 v168, v167, v171, v168
	v_mul_f32 v172, v159, v172
	v_add_f32_dpp v160, v160, v160 row_half_mirror row_mask:0xf bank_mask:0x5
	v_add_f32_dpp v160, v168, v168 row_half_mirror row_mask:0xf bank_mask:0xa
	v_mul_f32 v173, v164, v173
	v_mul_f32 v174, v165, v174
	v_add_f32_dpp v160, v160, v160 quad_perm:[1,0,3,2] row_mask:0xf bank_mask:0xf
	v_mul_f32 v175, v167, v175
	v_fma_f32 v172, v184, v180, v172
	v_add_f32_dpp v160, v160, v160 quad_perm:[2,3,0,1] row_mask:0xf bank_mask:0xf
	v_fma_f32 v173, v184, v181, v173
	v_fma_f32 v174, v184, v182, v174
	v_add_f32_dpp v160, v160, v160 row_ror:8 row_mask:0xf bank_mask:0xf
	v_fma_f32 v175, v184, v183, v175
	v_fma_f32 v168, v184, v186, v160
	v_mov_b32_dpp v160, v160 row_half_mirror row_mask:0xf bank_mask:0xa
	ds_read_b128 v[180:183], v3 offset:40960
	v_fma_f32 v159, -v160, v176, v172
	v_fma_f32 v164, -v160, v177, v173
	v_fma_f32 v165, -v160, v178, v174
	v_fma_f32 v167, -v160, v179, v175
	v_fma_f32 v168, -v160, v185, v168
	ds_read_b128 v[160:163], v3 offset:39936
	ds_write_b32 v2, v168 offset:1536
	ds_read_b128 v[168:171], v3 offset:40192
	ds_read_b128 v[172:175], v3 offset:40448
	ds_read_b128 v[184:187], v4 offset:39936
	ds_read_b128 v[176:179], v3 offset:40704
	s_waitcnt lgkmcnt(7)
	v_mul_f32 v188, v159, v188
	v_mul_f32 v192, v159, v192
	v_fma_f32 v188, v164, v189, v188
	v_fma_f32 v192, v164, v193, v192
	v_fma_f32 v188, v165, v190, v188
	v_fma_f32 v192, v165, v194, v192
	v_fma_f32 v188, v167, v191, v188
	v_fma_f32 v192, v167, v195, v192
	v_mul_f32 v196, v159, v196
	v_add_f32_dpp v188, v188, v188 row_half_mirror row_mask:0xf bank_mask:0x5
	v_add_f32_dpp v188, v192, v192 row_half_mirror row_mask:0xf bank_mask:0xa
	v_mul_f32 v197, v164, v197
	v_mul_f32 v198, v165, v198
	v_add_f32_dpp v188, v188, v188 quad_perm:[1,0,3,2] row_mask:0xf bank_mask:0xf
	v_mul_f32 v199, v167, v199
	v_fma_f32 v196, v208, v204, v196
	v_add_f32_dpp v188, v188, v188 quad_perm:[2,3,0,1] row_mask:0xf bank_mask:0xf
	v_fma_f32 v197, v208, v205, v197
	v_fma_f32 v198, v208, v206, v198
	v_add_f32_dpp v188, v188, v188 row_ror:8 row_mask:0xf bank_mask:0xf
	v_fma_f32 v199, v208, v207, v199
	v_fma_f32 v192, v208, v210, v188
	v_mov_b32_dpp v188, v188 row_half_mirror row_mask:0xf bank_mask:0xa
	ds_read_b128 v[204:207], v3 offset:42496
	v_fma_f32 v159, -v188, v200, v196
	v_fma_f32 v164, -v188, v201, v197
	v_fma_f32 v165, -v188, v202, v198
	v_fma_f32 v167, -v188, v203, v199
	v_fma_f32 v192, -v188, v209, v192
	ds_read_b128 v[188:191], v3 offset:41472
	ds_write_b32 v2, v192 offset:1600
	ds_read_b128 v[192:195], v3 offset:41728
	ds_read_b128 v[196:199], v3 offset:41984
	ds_read_b128 v[208:211], v4 offset:41472
	ds_read_b128 v[200:203], v3 offset:42240
	s_waitcnt lgkmcnt(7)
	v_mul_f32 v160, v159, v160
	v_mul_f32 v168, v159, v168
	v_fma_f32 v160, v164, v161, v160
	v_fma_f32 v168, v164, v169, v168
	v_fma_f32 v160, v165, v162, v160
	v_fma_f32 v168, v165, v170, v168
	v_fma_f32 v160, v167, v163, v160
	v_fma_f32 v168, v167, v171, v168
	v_mul_f32 v172, v159, v172
	v_add_f32_dpp v160, v160, v160 row_half_mirror row_mask:0xf bank_mask:0x5
	v_add_f32_dpp v160, v168, v168 row_half_mirror row_mask:0xf bank_mask:0xa
	v_mul_f32 v173, v164, v173
	v_mul_f32 v174, v165, v174
	v_add_f32_dpp v160, v160, v160 quad_perm:[1,0,3,2] row_mask:0xf bank_mask:0xf
	v_mul_f32 v175, v167, v175
	v_fma_f32 v172, v184, v180, v172
	v_add_f32_dpp v160, v160, v160 quad_perm:[2,3,0,1] row_mask:0xf bank_mask:0xf
	v_fma_f32 v173, v184, v181, v173
	v_fma_f32 v174, v184, v182, v174
	v_add_f32_dpp v160, v160, v160 row_ror:8 row_mask:0xf bank_mask:0xf
	v_fma_f32 v175, v184, v183, v175
	v_fma_f32 v168, v184, v186, v160
	v_mov_b32_dpp v160, v160 row_half_mirror row_mask:0xf bank_mask:0xa
	ds_read_b128 v[180:183], v3 offset:44032
	v_fma_f32 v159, -v160, v176, v172
	v_fma_f32 v164, -v160, v177, v173
	v_fma_f32 v165, -v160, v178, v174
	v_fma_f32 v167, -v160, v179, v175
	v_fma_f32 v168, -v160, v185, v168
	ds_read_b128 v[160:163], v3 offset:43008
	ds_write_b32 v2, v168 offset:1664
	ds_read_b128 v[168:171], v3 offset:43264
	ds_read_b128 v[172:175], v3 offset:43520
	ds_read_b128 v[184:187], v4 offset:43008
	ds_read_b128 v[176:179], v3 offset:43776
	s_waitcnt lgkmcnt(7)
; __device__ __forceinline__ float vfma(float a, float b, float c) { float d; asm("v_fma_f32 %0, %1, %2, %3" : "=v"(d) : "v"(a), "v"(b), "v"(c)); return d; }
; __device__ __forceinline__ float vnfma(float a, float b, float c) { float d; asm("v_fma_f32 %0, -%1, %2, %3" : "=v"(d) : "v"(a), "v"(b), "v"(c)); return d; }
; __device__ __forceinline__ float vmul(float a, float b) { float d; asm("v_mul_f32 %0, %1, %2" : "=v"(d) : "v"(a), "v"(b)); return d; }
; __device__ __forceinline__ float vadd(float a, float b) { float d; asm("v_add_f32 %0, %1, %2" : "=v"(d) : "v"(a), "v"(b)); return d; }
; __device__ __forceinline__ float step_compute(float (&S)[4], const StepOp& o) {
;     float d1 = vmul(S[0], o.kk[0]), d2 = vmul(S[0], o.wr[0]), e1 = vmul(S[1], o.kk[1]), e2 = vmul(S[1], o.wr[1]);
;     d1 = vfma(S[2], o.kk[2], d1); d2 = vfma(S[2], o.wr[2], d2); e1 = vfma(S[3], o.kk[3], e1); e2 = vfma(S[3], o.wr[3], e2);
;     d1 = vadd(d1, e1); d2 = vadd(d2, e2);
;     float t0, t1, t2, t3;
;     asm volatile(
;         "v_mul_f32 %[t0], %[s0], %[w0]\n\t"
;         "v_mul_f32 %[t1], %[s1], %[w1]\n\t"
;         "v_add_f32_dpp %[d1], %[d1], %[d1] quad_perm:[1,0,3,2] row_mask:0xf bank_mask:0xf bound_ctrl:1\n\t"
;         "v_add_f32_dpp %[d2], %[d2], %[d2] quad_perm:[1,0,3,2] row_mask:0xf bank_mask:0xf bound_ctrl:1\n\t"
;         "v_mul_f32 %[t2], %[s2], %[w2]\n\t"
;         "v_add_f32_dpp %[d1], %[d1], %[d1] quad_perm:[2,3,0,1] row_mask:0xf bank_mask:0xf bound_ctrl:1\n\t"
;         "v_add_f32_dpp %[d2], %[d2], %[d2] quad_perm:[2,3,0,1] row_mask:0xf bank_mask:0xf bound_ctrl:1\n\t"
;         "v_mul_f32 %[t3], %[s3], %[w3]\n\t"
;         "v_add_f32_dpp %[d1], %[d1], %[d1] row_half_mirror row_mask:0xf bank_mask:0xf bound_ctrl:1\n\t"
;         "v_add_f32_dpp %[d2], %[d2], %[d2] row_half_mirror row_mask:0xf bank_mask:0xf bound_ctrl:1\n\t"
;         "v_fma_f32 %[t0], %[v], %[k0], %[t0]\n\t"
;         "v_add_f32_dpp %[d1], %[d1], %[d1] row_mirror row_mask:0xf bank_mask:0xf bound_ctrl:1\n\t"
;         "v_add_f32_dpp %[d2], %[d2], %[d2] row_mirror row_mask:0xf bank_mask:0xf bound_ctrl:1\n\t"
;         "v_fma_f32 %[t1], %[v], %[k1], %[t1]\n\t"
;         "v_fma_f32 %[t2], %[v], %[k2], %[t2]\n\t"
;         "v_fma_f32 %[t3], %[v], %[k3], %[t3]"
;         : [t0] "=&v"(t0), [t1] "=&v"(t1), [t2] "=&v"(t2), [t3] "=&v"(t3), [d1] "+v"(d1), [d2] "+v"(d2)
	v_mul_f32 v188, v159, v188
	v_mul_f32 v192, v159, v192
	v_fma_f32 v188, v164, v189, v188
	v_fma_f32 v192, v164, v193, v192
	v_fma_f32 v188, v165, v190, v188
	v_fma_f32 v192, v165, v194, v192
	v_fma_f32 v188, v167, v191, v188
	v_fma_f32 v192, v167, v195, v192
	v_mul_f32 v196, v159, v196
	v_add_f32_dpp v188, v188, v188 row_half_mirror row_mask:0xf bank_mask:0x5
	v_add_f32_dpp v188, v192, v192 row_half_mirror row_mask:0xf bank_mask:0xa
	v_mul_f32 v197, v164, v197
	v_mul_f32 v198, v165, v198
	v_add_f32_dpp v188, v188, v188 quad_perm:[1,0,3,2] row_mask:0xf bank_mask:0xf
	v_mul_f32 v199, v167, v199
	v_fma_f32 v196, v208, v204, v196
	v_add_f32_dpp v188, v188, v188 quad_perm:[2,3,0,1] row_mask:0xf bank_mask:0xf
	v_fma_f32 v197, v208, v205, v197
	v_fma_f32 v198, v208, v206, v198
	v_add_f32_dpp v188, v188, v188 row_ror:8 row_mask:0xf bank_mask:0xf
	v_fma_f32 v199, v208, v207, v199
	v_fma_f32 v192, v208, v210, v188
	v_mov_b32_dpp v188, v188 row_half_mirror row_mask:0xf bank_mask:0xa
	ds_read_b128 v[204:207], v3 offset:45568
	v_fma_f32 v159, -v188, v200, v196
	v_fma_f32 v164, -v188, v201, v197
	v_fma_f32 v165, -v188, v202, v198
	v_fma_f32 v167, -v188, v203, v199
	v_fma_f32 v192, -v188, v209, v192
	ds_read_b128 v[188:191], v3 offset:44544
	ds_write_b32 v2, v192 offset:1728
	ds_read_b128 v[192:195], v3 offset:44800
	ds_read_b128 v[196:199], v3 offset:45056
	ds_read_b128 v[208:211], v4 offset:44544
	ds_read_b128 v[200:203], v3 offset:45312
	s_waitcnt lgkmcnt(7)
	v_mul_f32 v160, v159, v160
	v_mul_f32 v168, v159, v168
	v_fma_f32 v160, v164, v161, v160
	v_fma_f32 v168, v164, v169, v168
	v_fma_f32 v160, v165, v162, v160
	v_fma_f32 v168, v165, v170, v168
	v_fma_f32 v160, v167, v163, v160
	v_fma_f32 v168, v167, v171, v168
	v_mul_f32 v172, v159, v172
	v_add_f32_dpp v160, v160, v160 row_half_mirror row_mask:0xf bank_mask:0x5
	v_add_f32_dpp v160, v168, v168 row_half_mirror row_mask:0xf bank_mask:0xa
	v_mul_f32 v173, v164, v173
	v_mul_f32 v174, v165, v174
	v_add_f32_dpp v160, v160, v160 quad_perm:[1,0,3,2] row_mask:0xf bank_mask:0xf
	v_mul_f32 v175, v167, v175
	v_fma_f32 v172, v184, v180, v172
	v_add_f32_dpp v160, v160, v160 quad_perm:[2,3,0,1] row_mask:0xf bank_mask:0xf
	v_fma_f32 v173, v184, v181, v173
	v_fma_f32 v174, v184, v182, v174
	v_add_f32_dpp v160, v160, v160 row_ror:8 row_mask:0xf bank_mask:0xf
	v_fma_f32 v175, v184, v183, v175
	v_fma_f32 v168, v184, v186, v160
	v_mov_b32_dpp v160, v160 row_half_mirror row_mask:0xf bank_mask:0xa
	ds_read_b128 v[180:183], v3 offset:47104
	v_fma_f32 v159, -v160, v176, v172
	v_fma_f32 v164, -v160, v177, v173
	v_fma_f32 v165, -v160, v178, v174
	v_fma_f32 v167, -v160, v179, v175
	v_fma_f32 v168, -v160, v185, v168
	ds_read_b128 v[160:163], v3 offset:46080
	ds_write_b32 v2, v168 offset:1792
	ds_read_b128 v[168:171], v3 offset:46336
	ds_read_b128 v[172:175], v3 offset:46592
	ds_read_b128 v[184:187], v4 offset:46080
	ds_read_b128 v[176:179], v3 offset:46848
	s_waitcnt lgkmcnt(7)
	v_mul_f32 v188, v159, v188
	v_mul_f32 v192, v159, v192
	v_fma_f32 v188, v164, v189, v188
	v_fma_f32 v192, v164, v193, v192
	v_fma_f32 v188, v165, v190, v188
	v_fma_f32 v192, v165, v194, v192
	v_fma_f32 v188, v167, v191, v188
	v_fma_f32 v192, v167, v195, v192
	v_mul_f32 v196, v159, v196
	v_add_f32_dpp v188, v188, v188 row_half_mirror row_mask:0xf bank_mask:0x5
	v_add_f32_dpp v188, v192, v192 row_half_mirror row_mask:0xf bank_mask:0xa
	v_mul_f32 v197, v164, v197
	v_mul_f32 v198, v165, v198
	v_add_f32_dpp v188, v188, v188 quad_perm:[1,0,3,2] row_mask:0xf bank_mask:0xf
	v_mul_f32 v199, v167, v199
	v_fma_f32 v196, v208, v204, v196
	v_add_f32_dpp v188, v188, v188 quad_perm:[2,3,0,1] row_mask:0xf bank_mask:0xf
	v_fma_f32 v197, v208, v205, v197
	v_fma_f32 v198, v208, v206, v198
	v_add_f32_dpp v188, v188, v188 row_ror:8 row_mask:0xf bank_mask:0xf
	v_fma_f32 v199, v208, v207, v199
	v_fma_f32 v192, v208, v210, v188
	v_mov_b32_dpp v188, v188 row_half_mirror row_mask:0xf bank_mask:0xa
	ds_read_b128 v[204:207], v3 offset:48640
	v_fma_f32 v159, -v188, v200, v196
	v_fma_f32 v164, -v188, v201, v197
	v_fma_f32 v165, -v188, v202, v198
	v_fma_f32 v167, -v188, v203, v199
	v_fma_f32 v192, -v188, v209, v192
	ds_read_b128 v[188:191], v3 offset:47616
	ds_write_b32 v2, v192 offset:1856
	ds_read_b128 v[192:195], v3 offset:47872
	ds_read_b128 v[196:199], v3 offset:48128
	ds_read_b128 v[208:211], v4 offset:47616
	ds_read_b128 v[200:203], v3 offset:48384
	s_waitcnt lgkmcnt(7)
	v_mul_f32 v160, v159, v160
	v_mul_f32 v168, v159, v168
	v_fma_f32 v160, v164, v161, v160
	v_fma_f32 v168, v164, v169, v168
	v_fma_f32 v160, v165, v162, v160
	v_fma_f32 v168, v165, v170, v168
	v_fma_f32 v160, v167, v163, v160
	v_fma_f32 v168, v167, v171, v168
	v_mul_f32 v172, v159, v172
	v_add_f32_dpp v160, v160, v160 row_half_mirror row_mask:0xf bank_mask:0x5
	v_add_f32_dpp v160, v168, v168 row_half_mirror row_mask:0xf bank_mask:0xa
	v_mul_f32 v173, v164, v173
	v_mul_f32 v174, v165, v174
	v_add_f32_dpp v160, v160, v160 quad_perm:[1,0,3,2] row_mask:0xf bank_mask:0xf
	v_mul_f32 v175, v167, v175
	v_fma_f32 v172, v184, v180, v172
	v_add_f32_dpp v160, v160, v160 quad_perm:[2,3,0,1] row_mask:0xf bank_mask:0xf
	v_fma_f32 v173, v184, v181, v173
	v_fma_f32 v174, v184, v182, v174
	v_add_f32_dpp v160, v160, v160 row_ror:8 row_mask:0xf bank_mask:0xf
	v_fma_f32 v175, v184, v183, v175
	v_fma_f32 v168, v184, v186, v160
	v_mov_b32_dpp v160, v160 row_half_mirror row_mask:0xf bank_mask:0xa
	v_fma_f32 v159, -v160, v176, v172
	v_fma_f32 v164, -v160, v177, v173
	v_fma_f32 v165, -v160, v178, v174
	v_fma_f32 v167, -v160, v179, v175
	v_fma_f32 v168, -v160, v185, v168
	ds_write_b32 v2, v168 offset:1920
	s_waitcnt lgkmcnt(1)
	v_mul_f32 v188, v159, v188
	v_mul_f32 v192, v159, v192
	v_fma_f32 v188, v164, v189, v188
	v_fma_f32 v192, v164, v193, v192
	v_fma_f32 v188, v165, v190, v188
	v_fma_f32 v192, v165, v194, v192
	v_fma_f32 v188, v167, v191, v188
	v_fma_f32 v192, v167, v195, v192
	v_mul_f32 v196, v159, v196
	v_add_f32_dpp v188, v188, v188 row_half_mirror row_mask:0xf bank_mask:0x5
	v_add_f32_dpp v188, v192, v192 row_half_mirror row_mask:0xf bank_mask:0xa
	v_mul_f32 v197, v164, v197
	v_mul_f32 v198, v165, v198
	v_add_f32_dpp v188, v188, v188 quad_perm:[1,0,3,2] row_mask:0xf bank_mask:0xf
	v_mul_f32 v199, v167, v199
	v_fma_f32 v196, v208, v204, v196
	v_add_f32_dpp v188, v188, v188 quad_perm:[2,3,0,1] row_mask:0xf bank_mask:0xf
	v_fma_f32 v197, v208, v205, v197
	v_fma_f32 v198, v208, v206, v198
	v_add_f32_dpp v188, v188, v188 row_ror:8 row_mask:0xf bank_mask:0xf
	v_fma_f32 v199, v208, v207, v199
	v_fma_f32 v192, v208, v210, v188
	v_mov_b32_dpp v188, v188 row_half_mirror row_mask:0xf bank_mask:0xa
	v_fma_f32 v3, -v188, v200, v196
	v_fma_f32 v4, -v188, v201, v197
	v_fma_f32 v115, -v188, v202, v198
	v_fma_f32 v159, -v188, v203, v199
	v_fma_f32 v192, -v188, v209, v192
	ds_write_b32 v2, v192 offset:1984
